# in-proj epilogue: QK-norm row sums by permlane16/32 swaps and V-transpose lane-pair exchange by DPP quad_perm instead of 144 ds_bpermute round trips
# baseline (speedup 1.0000x reference)
;     DI void operator()(const AccT& acc, const Unit& u, int wr, int wc, int fr, int fq, LAS unsigned char*) const {
;     ...
;                 if (donorm) {
;                     float ss = 0.f;
; #pragma unroll
;                     for (int bj = 0; bj < 2; ++bj)
; #pragma unroll
;                         for (int n = 0; n < 2; ++n) ss += (v[bj][n][0] * v[bj][n][0] + v[bj][n][1] * v[bj][n][1]) + (v[bj][n][2] * v[bj][n][2] + v[bj][n][3] * v[bj][n][3]);
;                     ss += __shfl_xor(ss, 16); ss += __shfl_xor(ss, 32);
;                     const float rs = rsqrtf(ss * (1.f / 64.f) + EPS);
; #pragma unroll
;                     for (int bj = 0; bj < 2; ++bj)
; #pragma unroll
;                         for (int n = 0; n < 2; ++n) v[bj][n] = v[bj][n] * rs * gv[bj][n];
;                 }
.LBB0_131:
	s_and_b64 vcc, exec, s[6:7]
	s_cbranch_vccnz .LBB0_133
	v_pk_mul_f32 v[182:183], v[142:143], v[142:143]
	v_pk_mul_f32 v[184:185], v[140:141], v[140:141]
	v_mul_f32_e32 v150, v132, v132
	v_pk_mov_b32 v[186:187], v[184:185], v[182:183] op_sel:[1,0]
	v_mov_b32_e32 v185, v183
	v_pk_add_f32 v[182:183], v[186:187], v[184:185]
	v_pk_mul_f32 v[184:185], v[138:139], v[138:139]
	v_pk_mul_f32 v[186:187], v[136:137], v[136:137]
	v_pk_add_f32 v[182:183], v[182:183], v[182:183] op_sel_hi:[0,1]
	v_pk_mov_b32 v[188:189], v[186:187], v[184:185] op_sel:[1,0]
	v_mov_b32_e32 v187, v185
	v_pk_add_f32 v[184:185], v[188:189], v[186:187]
	v_pk_fma_f32 v[186:187], v[132:133], v[132:133], v[150:151] op_sel_hi:[1,1,0]
	v_mul_f32_e32 v150, v134, v134
	v_pk_add_f32 v[184:185], v[184:185], v[184:185] op_sel_hi:[0,1]
	v_pk_fma_f32 v[188:189], v[134:135], v[134:135], v[150:151] op_sel_hi:[1,1,0]
	v_mul_f32_e32 v186, v128, v128
	v_mul_f32_e32 v188, v129, v129
	v_mul_f32_e32 v184, v130, v130
	v_mul_f32_e32 v182, v131, v131
	v_pk_add_f32 v[186:187], v[186:187], v[188:189]
	v_pk_add_f32 v[182:183], v[184:185], v[182:183]
	s_nop 0
	v_pk_add_f32 v[182:183], v[186:187], v[182:183]
	s_nop 0
	v_add_f32_e32 v150, v182, v183
	v_and_b32_e32 v183, 64, v198
	v_add_u32_e32 v183, 64, v183
	v_mov_b32_e32 v182, v150
	s_nop 1
	v_permlane16_swap_b32_e32 v182, v150
	v_add_f32_e32 v150, v150, v182
	v_mov_b32_e32 v182, v150
	s_nop 1
	v_permlane32_swap_b32_e32 v182, v150
	s_waitcnt lgkmcnt(0)
	v_add_f32_e32 v150, v150, v182
	v_fmamk_f32 v150, v150, 0x3c800000, v195
	v_mul_f32_e32 v182, 0x4b800000, v150
	v_cmp_gt_f32_e32 vcc, s78, v150
	s_nop 1
	v_cndmask_b32_e32 v150, v150, v182, vcc
	v_rsq_f32_e32 v150, v150
	s_nop 0
	v_mul_f32_e32 v182, 0x45800000, v150
	v_cndmask_b32_e32 v150, v150, v182, vcc
	v_pk_mul_f32 v[140:141], v[140:141], v[150:151] op_sel_hi:[1,0]
	v_pk_mul_f32 v[142:143], v[142:143], v[150:151] op_sel_hi:[1,0]
	v_pk_mul_f32 v[136:137], v[136:137], v[150:151] op_sel_hi:[1,0]
	v_pk_mul_f32 v[138:139], v[138:139], v[150:151] op_sel_hi:[1,0]
	v_pk_mul_f32 v[132:133], v[132:133], v[150:151] op_sel_hi:[1,0]
	v_pk_mul_f32 v[134:135], v[134:135], v[150:151] op_sel_hi:[1,0]
	v_pk_mul_f32 v[128:129], v[128:129], v[150:151] op_sel_hi:[1,0]
	v_pk_mul_f32 v[130:131], v[130:131], v[150:151] op_sel_hi:[1,0]
	s_waitcnt vmcnt(0)
	v_pk_mul_f32 v[142:143], v[54:55], v[142:143]
	v_pk_mul_f32 v[140:141], v[52:53], v[140:141]
	v_pk_mul_f32 v[138:139], v[50:51], v[138:139]
	v_pk_mul_f32 v[136:137], v[48:49], v[136:137]
	v_pk_mul_f32 v[134:135], v[62:63], v[134:135]
	v_pk_mul_f32 v[132:133], v[60:61], v[132:133]
	v_pk_mul_f32 v[130:131], v[58:59], v[130:131]
	v_pk_mul_f32 v[128:129], v[56:57], v[128:129]

; DI u32x2 pk4(f32x4 v) { u32x2 r; r.x = pk2(v[0], v[1]); r.y = pk2(v[2], v[3]); return r; }
;     DI void operator()(const AccT& acc, const Unit& u, int wr, int wc, int fr, int fq, LAS unsigned char*) const {
;     ...
;                     const bool isA = (kind == 1 || kind == 2), isK = (kind == 1 || kind == 4);
;                     const int srow = row - SEQ;
;                     const int band = isA ? 576 : 192, past = isA ? 512 : 128, nh = isA ? 8 : 2;
;                     const int krow = row < SEQ ? row : SEQ + (srow >> 6) * band + past + (srow & 63);
;                     const int krows = isA ? KA_ROWS : KB_ROWS;
;                     float* op = nullptr;
;                     size_t ooff = 0; bool has_o = false;
;                     if (row >= SEQ) { ooff = (isA ? (isK ? OFF_AKS : OFF_AVS) : (isK ? OFF_BKS : OFF_BVS)) + ((size_t)srow * nh + h) * 64; has_o = true; }
;                     else if (row >= SEQ - past) { ooff = (isA ? (isK ? OFF_AKP : OFF_AVP) : (isK ? OFF_BKP : OFF_BVP)) + ((size_t)(row - (SEQ - past)) * nh + h) * 64; has_o = true; }
;                     op = out + ooff;
;                     if (has_o) {
; #pragma unroll
;                         for (int bj = 0; bj < 2; ++bj)
; #pragma unroll
;                             for (int n = 0; n < 2; ++n) *(f32x4*)(op + 32 * bj + 16 * n + 4 * fq) = v[bj][n];
;                     }
;                     if (isK) {
;                         bf16_t* kp = (bf16_t*)(ws + (isA ? WS_KA : WS_KB));
; #pragma unroll
;                         for (int bj = 0; bj < 2; ++bj)
; #pragma unroll
;                             for (int n = 0; n < 2; ++n) *(u32x2*)(kp + kf_off(h, krows >> 5, krow, 32 * bj + 16 * n + 4 * fq)) = pk4(v[bj][n]);
;                     } else {
;                         bf16_t* vp = (bf16_t*)(ws + (isA ? WS_VTA : WS_VTB));
; #pragma unroll
;                         for (int bj = 0; bj < 2; ++bj)
; #pragma unroll
;                             for (int n = 0; n < 2; ++n)
; #pragma unroll
;                                 for (int j = 0; j < 4; ++j) {
;                                     const float mine = v[bj][n][j], oth = __shfl_xor(mine, 1);
;                                     if (!(fr & 1)) *(unsigned*)(vp + vf_off(h, krows >> 5, krow, 32 * bj + 16 * n + 4 * fq + j)) = pk2(mine, oth);
;                                 }
.LBB0_142:
	s_or_b64 exec, exec, s[10:11]
	v_lshrrev_b32_e32 v183, 6, v183
	v_or_b32_e32 v150, s90, v167
	v_mad_u64_u32 v[184:185], s[10:11], s31, v183, v[150:151]
	v_cmp_gt_i32_e32 vcc, s68, v182
	s_mov_b64 s[10:11], -1
	s_nop 0
	v_cndmask_b32_e32 v183, v184, v182, vcc
	v_ashrrev_i32_e32 v184, 5, v183
	s_and_b64 vcc, exec, s[50:51]
	v_ashrrev_i32_e32 v185, 31, v184
	s_cbranch_vccz .LBB0_176
	v_and_b32_e32 v186, 64, v198
	v_xor_b32_e32 v150, 1, v198
	v_add_u32_e32 v186, 64, v186
	v_cmp_lt_i32_e32 vcc, v150, v186
	s_add_u32 s10, s36, s91
	s_addc_u32 s11, s37, 0
	v_cndmask_b32_e32 v150, v198, v150, vcc
	v_lshlrev_b32_e32 v199, 2, v150
	v_lshlrev_b32_e32 v150, 3, v183
	v_and_b32_e32 v201, 32, v150
	v_and_b32_e32 v200, 3, v183
	v_and_b32_e32 v150, 8, v183
	v_lshl_add_u64 v[186:187], s[10:11], 0, v[150:151]
	v_lshlrev_b32_e32 v150, 1, v200
	v_mov_b32_dpp v200, v140 quad_perm:[1,0,3,2] row_mask:0xf bank_mask:0xf
	v_lshl_add_u64 v[188:189], s[46:47], 0, v[184:185]
	v_lshl_add_u64 v[186:187], v[186:187], 0, v[150:151]
	v_lshlrev_b32_e32 v150, 2, v183
	v_lshlrev_b64 v[188:189], 8, v[188:189]
	v_and_b32_e32 v150, 64, v150
	v_or3_b32 v150, v188, v150, v201
	s_and_saveexec_b64 s[10:11], s[12:13]
	s_cbranch_execz .LBB0_145
	v_or_b32_e32 v188, v150, v152
	s_waitcnt lgkmcnt(0)
	v_cvt_pk_bf16_f32 v202, v140, v200
	v_lshl_add_u64 v[200:201], v[188:189], 4, v[186:187]
	global_store_dword v[200:201], v202, off
.LBB0_145:
	s_or_b64 exec, exec, s[10:11]
	v_mov_b32_dpp v188, v141 quad_perm:[1,0,3,2] row_mask:0xf bank_mask:0xf
	s_and_saveexec_b64 s[10:11], s[12:13]
	s_cbranch_execz .LBB0_147
	s_waitcnt lgkmcnt(0)
	v_cvt_pk_bf16_f32 v202, v141, v188
	v_or_b32_e32 v188, v150, v154
	v_lshl_add_u64 v[200:201], v[188:189], 4, v[186:187]
	global_store_dword v[200:201], v202, off
.LBB0_147:
	s_or_b64 exec, exec, s[10:11]
	s_waitcnt lgkmcnt(0)
	v_mov_b32_dpp v188, v142 quad_perm:[1,0,3,2] row_mask:0xf bank_mask:0xf
	s_and_saveexec_b64 s[10:11], s[12:13]
	s_cbranch_execz .LBB0_149
	s_waitcnt lgkmcnt(0)
	v_cvt_pk_bf16_f32 v202, v142, v188
	v_or_b32_e32 v188, v150, v156
	v_lshl_add_u64 v[200:201], v[188:189], 4, v[186:187]
	global_store_dword v[200:201], v202, off
.LBB0_149:
	s_or_b64 exec, exec, s[10:11]
	s_waitcnt lgkmcnt(0)
	v_mov_b32_dpp v188, v143 quad_perm:[1,0,3,2] row_mask:0xf bank_mask:0xf
	s_and_saveexec_b64 s[10:11], s[12:13]
	s_cbranch_execz .LBB0_151
	s_waitcnt lgkmcnt(0)
	v_cvt_pk_bf16_f32 v202, v143, v188
	v_or_b32_e32 v188, v150, v158
	v_lshl_add_u64 v[200:201], v[188:189], 4, v[186:187]
	global_store_dword v[200:201], v202, off
.LBB0_151:
	s_or_b64 exec, exec, s[10:11]
	s_waitcnt lgkmcnt(0)
	v_mov_b32_dpp v188, v136 quad_perm:[1,0,3,2] row_mask:0xf bank_mask:0xf
	s_and_saveexec_b64 s[10:11], s[12:13]
	s_cbranch_execz .LBB0_153
	s_waitcnt lgkmcnt(0)
	v_cvt_pk_bf16_f32 v202, v136, v188
	v_or_b32_e32 v188, v150, v160
	v_lshl_add_u64 v[200:201], v[188:189], 4, v[186:187]
	global_store_dword v[200:201], v202, off
.LBB0_153:
	s_or_b64 exec, exec, s[10:11]
	s_waitcnt lgkmcnt(0)
	v_mov_b32_dpp v188, v137 quad_perm:[1,0,3,2] row_mask:0xf bank_mask:0xf
	s_and_saveexec_b64 s[10:11], s[12:13]
	s_cbranch_execz .LBB0_155
	s_waitcnt lgkmcnt(0)
	v_cvt_pk_bf16_f32 v202, v137, v188
	v_or_b32_e32 v188, v150, v162
	v_lshl_add_u64 v[200:201], v[188:189], 4, v[186:187]
	global_store_dword v[200:201], v202, off
.LBB0_155:
	s_or_b64 exec, exec, s[10:11]
	s_waitcnt lgkmcnt(0)
	v_mov_b32_dpp v188, v138 quad_perm:[1,0,3,2] row_mask:0xf bank_mask:0xf
	s_and_saveexec_b64 s[10:11], s[12:13]
	s_cbranch_execz .LBB0_157
	s_waitcnt lgkmcnt(0)
	v_cvt_pk_bf16_f32 v202, v138, v188
	v_or_b32_e32 v188, v150, v164
	v_lshl_add_u64 v[200:201], v[188:189], 4, v[186:187]
	global_store_dword v[200:201], v202, off
; DI size_t vf_off(int h, int nblk, int krow, int d) { const int kk = krow & 31; return (((((size_t)h * nblk + (krow >> 5)) * 2 + (d >> 5)) * 2 + (kk >> 4)) * 64 + ((kk >> 2) & 1) * 32 + (d & 31)) * 8 + 4 * ((kk >> 3) & 1) + (kk & 3); }
;     DI void operator()(const AccT& acc, const Unit& u, int wr, int wc, int fr, int fq, LAS unsigned char*) const {
;     ...
;                     } else {
;                         bf16_t* vp = (bf16_t*)(ws + (isA ? WS_VTA : WS_VTB));
; #pragma unroll
;                         for (int bj = 0; bj < 2; ++bj)
; #pragma unroll
;                             for (int n = 0; n < 2; ++n)
; #pragma unroll
;                                 for (int j = 0; j < 4; ++j) {
;                                     const float mine = v[bj][n][j], oth = __shfl_xor(mine, 1);
;                                     if (!(fr & 1)) *(unsigned*)(vp + vf_off(h, krows >> 5, krow, 32 * bj + 16 * n + 4 * fq + j)) = pk2(mine, oth);
;                                 }
.LBB0_157:
	s_or_b64 exec, exec, s[10:11]
	s_waitcnt lgkmcnt(0)
	v_mov_b32_dpp v188, v139 quad_perm:[1,0,3,2] row_mask:0xf bank_mask:0xf
	s_and_saveexec_b64 s[10:11], s[12:13]
	s_cbranch_execz .LBB0_159
	s_waitcnt lgkmcnt(0)
	v_cvt_pk_bf16_f32 v202, v139, v188
	v_or_b32_e32 v188, v150, v166
	v_lshl_add_u64 v[200:201], v[188:189], 4, v[186:187]
	global_store_dword v[200:201], v202, off
.LBB0_159:
	s_or_b64 exec, exec, s[10:11]
	s_waitcnt lgkmcnt(0)
	v_mov_b32_dpp v188, v132 quad_perm:[1,0,3,2] row_mask:0xf bank_mask:0xf
	v_or_b32_e32 v150, 0x80, v150
	s_and_saveexec_b64 s[10:11], s[12:13]
	s_cbranch_execz .LBB0_161
	s_waitcnt lgkmcnt(0)
	v_cvt_pk_bf16_f32 v202, v132, v188
	v_or_b32_e32 v188, v150, v152
	v_lshl_add_u64 v[200:201], v[188:189], 4, v[186:187]
	global_store_dword v[200:201], v202, off
.LBB0_161:
	s_or_b64 exec, exec, s[10:11]
	s_waitcnt lgkmcnt(0)
	v_mov_b32_dpp v188, v133 quad_perm:[1,0,3,2] row_mask:0xf bank_mask:0xf
	s_and_saveexec_b64 s[10:11], s[12:13]
	s_cbranch_execz .LBB0_163
	s_waitcnt lgkmcnt(0)
	v_cvt_pk_bf16_f32 v202, v133, v188
	v_or_b32_e32 v188, v150, v154
	v_lshl_add_u64 v[200:201], v[188:189], 4, v[186:187]
	global_store_dword v[200:201], v202, off
.LBB0_163:
	s_or_b64 exec, exec, s[10:11]
	s_waitcnt lgkmcnt(0)
	v_mov_b32_dpp v188, v134 quad_perm:[1,0,3,2] row_mask:0xf bank_mask:0xf
	s_and_saveexec_b64 s[10:11], s[12:13]
	s_cbranch_execz .LBB0_165
	s_waitcnt lgkmcnt(0)
	v_cvt_pk_bf16_f32 v202, v134, v188
	v_or_b32_e32 v188, v150, v156
	v_lshl_add_u64 v[200:201], v[188:189], 4, v[186:187]
	global_store_dword v[200:201], v202, off
.LBB0_165:
	s_or_b64 exec, exec, s[10:11]
	s_waitcnt lgkmcnt(0)
	v_mov_b32_dpp v188, v135 quad_perm:[1,0,3,2] row_mask:0xf bank_mask:0xf
	s_and_saveexec_b64 s[10:11], s[12:13]
	s_cbranch_execz .LBB0_167
	s_waitcnt lgkmcnt(0)
	v_cvt_pk_bf16_f32 v202, v135, v188
	v_or_b32_e32 v188, v150, v158
	v_lshl_add_u64 v[200:201], v[188:189], 4, v[186:187]
	global_store_dword v[200:201], v202, off
.LBB0_167:
	s_or_b64 exec, exec, s[10:11]
	s_waitcnt lgkmcnt(0)
	v_mov_b32_dpp v188, v128 quad_perm:[1,0,3,2] row_mask:0xf bank_mask:0xf
	s_and_saveexec_b64 s[10:11], s[12:13]
	s_cbranch_execz .LBB0_169
	s_waitcnt lgkmcnt(0)
	v_cvt_pk_bf16_f32 v202, v128, v188
	v_or_b32_e32 v188, v150, v160
	v_lshl_add_u64 v[200:201], v[188:189], 4, v[186:187]
	global_store_dword v[200:201], v202, off
.LBB0_169:
	s_or_b64 exec, exec, s[10:11]
	s_waitcnt lgkmcnt(0)
	v_mov_b32_dpp v188, v129 quad_perm:[1,0,3,2] row_mask:0xf bank_mask:0xf
	s_and_saveexec_b64 s[10:11], s[12:13]
	s_cbranch_execz .LBB0_171
	s_waitcnt lgkmcnt(0)
	v_cvt_pk_bf16_f32 v202, v129, v188
	v_or_b32_e32 v188, v150, v162
	v_lshl_add_u64 v[200:201], v[188:189], 4, v[186:187]
	global_store_dword v[200:201], v202, off
.LBB0_171:
	s_or_b64 exec, exec, s[10:11]
	s_waitcnt lgkmcnt(0)
	v_mov_b32_dpp v188, v130 quad_perm:[1,0,3,2] row_mask:0xf bank_mask:0xf
	s_and_saveexec_b64 s[10:11], s[12:13]
	s_cbranch_execz .LBB0_173
	s_waitcnt lgkmcnt(0)
	v_cvt_pk_bf16_f32 v202, v130, v188
	v_or_b32_e32 v188, v150, v164
	v_lshl_add_u64 v[200:201], v[188:189], 4, v[186:187]
	global_store_dword v[200:201], v202, off
.LBB0_173:
	s_or_b64 exec, exec, s[10:11]
	s_waitcnt lgkmcnt(0)
	v_mov_b32_dpp v188, v131 quad_perm:[1,0,3,2] row_mask:0xf bank_mask:0xf
	s_and_saveexec_b64 s[10:11], s[12:13]
	s_cbranch_execz .LBB0_175
	s_waitcnt lgkmcnt(0)
	v_cvt_pk_bf16_f32 v199, v131, v188
	v_or_b32_e32 v188, v150, v166
	v_lshl_add_u64 v[186:187], v[188:189], 4, v[186:187]
	global_store_dword v[186:187], v199, off

;     DI void operator()(const AccT& acc, const Unit& u, int wr, int wc, int fr, int fq, LAS unsigned char*) const {
;     ...
;                 if (donorm) {
;                     float ss = 0.f;
; #pragma unroll
;                     for (int bj = 0; bj < 2; ++bj)
; #pragma unroll
;                         for (int n = 0; n < 2; ++n) ss += (v[bj][n][0] * v[bj][n][0] + v[bj][n][1] * v[bj][n][1]) + (v[bj][n][2] * v[bj][n][2] + v[bj][n][3] * v[bj][n][3]);
;                     ss += __shfl_xor(ss, 16); ss += __shfl_xor(ss, 32);
;                     const float rs = rsqrtf(ss * (1.f / 64.f) + EPS);
; #pragma unroll
;                     for (int bj = 0; bj < 2; ++bj)
; #pragma unroll
;                         for (int n = 0; n < 2; ++n) v[bj][n] = v[bj][n] * rs * gv[bj][n];
;                 }
.LBB0_180:
	v_pk_mul_f32 v[128:129], v[126:127], v[126:127]
	v_pk_mul_f32 v[130:131], v[124:125], v[124:125]
	s_nop 0
	v_pk_mov_b32 v[132:133], v[130:131], v[128:129] op_sel:[1,0]
	v_mov_b32_e32 v131, v129
	v_pk_add_f32 v[128:129], v[132:133], v[130:131]
	v_pk_mul_f32 v[130:131], v[122:123], v[122:123]
	v_pk_add_f32 v[128:129], v[128:129], v[128:129] op_sel_hi:[0,1]
	v_pk_mul_f32 v[132:133], v[120:121], v[120:121]
	v_mul_f32_e32 v128, v116, v116
	v_pk_mov_b32 v[134:135], v[132:133], v[130:131] op_sel:[1,0]
	v_mov_b32_e32 v133, v131
	v_pk_add_f32 v[130:131], v[134:135], v[132:133]
	v_pk_fma_f32 v[132:133], v[116:117], v[116:117], v[128:129] op_sel_hi:[1,1,0]
	v_mul_f32_e32 v128, v118, v118
	v_pk_add_f32 v[130:131], v[130:131], v[130:131] op_sel_hi:[0,1]
	v_pk_fma_f32 v[134:135], v[118:119], v[118:119], v[128:129] op_sel_hi:[1,1,0]
	v_mul_f32_e32 v132, v112, v112
	v_mul_f32_e32 v134, v113, v113
	v_mul_f32_e32 v130, v114, v114
	v_mul_f32_e32 v128, v115, v115
	v_pk_add_f32 v[132:133], v[132:133], v[134:135]
	v_pk_add_f32 v[128:129], v[130:131], v[128:129]
	v_and_b32_e32 v130, 64, v198
	v_pk_add_f32 v[128:129], v[132:133], v[128:129]
	v_add_u32_e32 v130, 64, v130
	v_add_f32_e32 v128, v128, v129
	v_mov_b32_e32 v129, v128
	s_nop 1
	v_permlane16_swap_b32_e32 v129, v128
	v_add_f32_e32 v128, v128, v129
	v_mov_b32_e32 v129, v128
	s_nop 1
	v_permlane32_swap_b32_e32 v129, v128
	s_waitcnt lgkmcnt(0)
	v_add_f32_e32 v128, v128, v129
	v_fmamk_f32 v128, v128, 0x3c800000, v195
	v_mul_f32_e32 v129, 0x4b800000, v128
	v_cmp_gt_f32_e32 vcc, s78, v128
	s_nop 1
	v_cndmask_b32_e32 v128, v128, v129, vcc
	v_rsq_f32_e32 v128, v128
	s_nop 0
	v_mul_f32_e32 v129, 0x45800000, v128
	v_cndmask_b32_e32 v128, v128, v129, vcc
	v_pk_mul_f32 v[124:125], v[124:125], v[128:129] op_sel_hi:[1,0]
	v_pk_mul_f32 v[126:127], v[126:127], v[128:129] op_sel_hi:[1,0]
	v_pk_mul_f32 v[120:121], v[120:121], v[128:129] op_sel_hi:[1,0]
	v_pk_mul_f32 v[122:123], v[122:123], v[128:129] op_sel_hi:[1,0]
	v_pk_mul_f32 v[116:117], v[116:117], v[128:129] op_sel_hi:[1,0]
	v_pk_mul_f32 v[118:119], v[118:119], v[128:129] op_sel_hi:[1,0]
	v_pk_mul_f32 v[112:113], v[112:113], v[128:129] op_sel_hi:[1,0]
	v_pk_mul_f32 v[114:115], v[114:115], v[128:129] op_sel_hi:[1,0]
	s_waitcnt vmcnt(0)
	v_pk_mul_f32 v[126:127], v[54:55], v[126:127]
	v_pk_mul_f32 v[124:125], v[52:53], v[124:125]
	v_pk_mul_f32 v[122:123], v[50:51], v[122:123]
	v_pk_mul_f32 v[120:121], v[48:49], v[120:121]
	v_pk_mul_f32 v[118:119], v[62:63], v[118:119]
	v_pk_mul_f32 v[116:117], v[60:61], v[116:117]
	v_pk_mul_f32 v[114:115], v[58:59], v[114:115]
	v_pk_mul_f32 v[112:113], v[56:57], v[112:113]
	s_and_b64 vcc, exec, s[8:9]
	v_or_b32_e32 v128, 16, v182
	s_cbranch_vccz .LBB0_184
	s_branch .LBB0_185

; DI u32x2 pk4(f32x4 v) { u32x2 r; r.x = pk2(v[0], v[1]); r.y = pk2(v[2], v[3]); return r; }
;     DI void operator()(const AccT& acc, const Unit& u, int wr, int wc, int fr, int fq, LAS unsigned char*) const {
;     ...
;                     const bool isA = (kind == 1 || kind == 2), isK = (kind == 1 || kind == 4);
;                     const int srow = row - SEQ;
;                     const int band = isA ? 576 : 192, past = isA ? 512 : 128, nh = isA ? 8 : 2;
;                     const int krow = row < SEQ ? row : SEQ + (srow >> 6) * band + past + (srow & 63);
;                     const int krows = isA ? KA_ROWS : KB_ROWS;
;                     float* op = nullptr;
;                     size_t ooff = 0; bool has_o = false;
;                     if (row >= SEQ) { ooff = (isA ? (isK ? OFF_AKS : OFF_AVS) : (isK ? OFF_BKS : OFF_BVS)) + ((size_t)srow * nh + h) * 64; has_o = true; }
;                     else if (row >= SEQ - past) { ooff = (isA ? (isK ? OFF_AKP : OFF_AVP) : (isK ? OFF_BKP : OFF_BVP)) + ((size_t)(row - (SEQ - past)) * nh + h) * 64; has_o = true; }
;                     op = out + ooff;
;                     if (has_o) {
; #pragma unroll
;                         for (int bj = 0; bj < 2; ++bj)
; #pragma unroll
;                             for (int n = 0; n < 2; ++n) *(f32x4*)(op + 32 * bj + 16 * n + 4 * fq) = v[bj][n];
;                     }
;                     if (isK) {
;                         bf16_t* kp = (bf16_t*)(ws + (isA ? WS_KA : WS_KB));
; #pragma unroll
;                         for (int bj = 0; bj < 2; ++bj)
; #pragma unroll
;                             for (int n = 0; n < 2; ++n) *(u32x2*)(kp + kf_off(h, krows >> 5, krow, 32 * bj + 16 * n + 4 * fq)) = pk4(v[bj][n]);
;                     } else {
;                         bf16_t* vp = (bf16_t*)(ws + (isA ? WS_VTA : WS_VTB));
; #pragma unroll
;                         for (int bj = 0; bj < 2; ++bj)
; #pragma unroll
;                             for (int n = 0; n < 2; ++n)
; #pragma unroll
;                                 for (int j = 0; j < 4; ++j) {
;                                     const float mine = v[bj][n][j], oth = __shfl_xor(mine, 1);
;                                     if (!(fr & 1)) *(unsigned*)(vp + vf_off(h, krows >> 5, krow, 32 * bj + 16 * n + 4 * fq + j)) = pk2(mine, oth);
;                                 }
.LBB0_192:
	s_or_b64 exec, exec, s[0:1]
	v_lshrrev_b32_e32 v129, 6, v129
	v_or_b32_e32 v130, s90, v191
	v_mad_u64_u32 v[130:131], s[0:1], s31, v129, v[130:131]
	v_cmp_gt_i32_e32 vcc, s68, v128
	s_mov_b64 s[0:1], -1
	s_nop 0
	v_cndmask_b32_e32 v129, v130, v128, vcc
	v_ashrrev_i32_e32 v130, 5, v129
	s_andn2_b64 vcc, exec, s[50:51]
	v_ashrrev_i32_e32 v131, 31, v130
	s_cbranch_vccnz .LBB0_226
	v_and_b32_e32 v133, 64, v198
	v_xor_b32_e32 v132, 1, v198
	v_add_u32_e32 v133, 64, v133
	v_cmp_lt_i32_e32 vcc, v132, v133
	s_add_u32 s0, s36, s91
	v_lshl_add_u64 v[134:135], s[46:47], 0, v[130:131]
	v_cndmask_b32_e32 v132, v198, v132, vcc
	v_lshlrev_b32_e32 v136, 2, v132
	v_mov_b32_dpp v139, v124 quad_perm:[1,0,3,2] row_mask:0xf bank_mask:0xf
	s_addc_u32 s1, s37, 0
	v_lshlrev_b32_e32 v137, 3, v129
	v_and_b32_e32 v138, 3, v129
	v_and_b32_e32 v150, 8, v129
	v_lshlrev_b64 v[134:135], 8, v[134:135]
	v_lshl_add_u64 v[132:133], s[0:1], 0, v[150:151]
	v_lshlrev_b32_e32 v150, 1, v138
	v_and_or_b32 v137, v137, 32, v134
	v_lshl_add_u64 v[132:133], v[132:133], 0, v[150:151]
	v_or_b32_e32 v138, 64, v137
	s_and_saveexec_b64 s[0:1], s[12:13]
	s_cbranch_execz .LBB0_195
	v_or_b32_e32 v134, v138, v152
	s_waitcnt lgkmcnt(0)
	v_cvt_pk_bf16_f32 v139, v124, v139
	v_lshl_add_u64 v[140:141], v[134:135], 4, v[132:133]
	global_store_dword v[140:141], v139, off
.LBB0_195:
	s_or_b64 exec, exec, s[0:1]
	v_mov_b32_dpp v134, v125 quad_perm:[1,0,3,2] row_mask:0xf bank_mask:0xf
	s_and_saveexec_b64 s[0:1], s[12:13]
	s_cbranch_execz .LBB0_197
	s_waitcnt lgkmcnt(0)
	v_cvt_pk_bf16_f32 v139, v125, v134
	v_or_b32_e32 v134, v138, v154
	v_lshl_add_u64 v[140:141], v[134:135], 4, v[132:133]
	global_store_dword v[140:141], v139, off
.LBB0_197:
	s_or_b64 exec, exec, s[0:1]
	s_waitcnt lgkmcnt(0)
	v_mov_b32_dpp v134, v126 quad_perm:[1,0,3,2] row_mask:0xf bank_mask:0xf
	s_and_saveexec_b64 s[0:1], s[12:13]
	s_cbranch_execz .LBB0_199
	s_waitcnt lgkmcnt(0)
	v_cvt_pk_bf16_f32 v139, v126, v134
	v_or_b32_e32 v134, v138, v156
	v_lshl_add_u64 v[140:141], v[134:135], 4, v[132:133]
	global_store_dword v[140:141], v139, off
.LBB0_199:
	s_or_b64 exec, exec, s[0:1]
	s_waitcnt lgkmcnt(0)
	v_mov_b32_dpp v134, v127 quad_perm:[1,0,3,2] row_mask:0xf bank_mask:0xf
	s_and_saveexec_b64 s[0:1], s[12:13]
	s_cbranch_execz .LBB0_201
	s_waitcnt lgkmcnt(0)
	v_cvt_pk_bf16_f32 v139, v127, v134
	v_or_b32_e32 v134, v138, v158
	v_lshl_add_u64 v[140:141], v[134:135], 4, v[132:133]
	global_store_dword v[140:141], v139, off
.LBB0_201:
	s_or_b64 exec, exec, s[0:1]
	s_waitcnt lgkmcnt(0)
	v_mov_b32_dpp v134, v120 quad_perm:[1,0,3,2] row_mask:0xf bank_mask:0xf
	s_and_saveexec_b64 s[0:1], s[12:13]
	s_cbranch_execz .LBB0_203
	s_waitcnt lgkmcnt(0)
	v_cvt_pk_bf16_f32 v139, v120, v134
	v_or_b32_e32 v134, v138, v160
	v_lshl_add_u64 v[140:141], v[134:135], 4, v[132:133]
	global_store_dword v[140:141], v139, off
.LBB0_203:
	s_or_b64 exec, exec, s[0:1]
	s_waitcnt lgkmcnt(0)
	v_mov_b32_dpp v134, v121 quad_perm:[1,0,3,2] row_mask:0xf bank_mask:0xf
	s_and_saveexec_b64 s[0:1], s[12:13]
	s_cbranch_execz .LBB0_205
	s_waitcnt lgkmcnt(0)
	v_cvt_pk_bf16_f32 v139, v121, v134
	v_or_b32_e32 v134, v138, v162
	v_lshl_add_u64 v[140:141], v[134:135], 4, v[132:133]
	global_store_dword v[140:141], v139, off
.LBB0_205:
	s_or_b64 exec, exec, s[0:1]
	s_waitcnt lgkmcnt(0)
	v_mov_b32_dpp v134, v122 quad_perm:[1,0,3,2] row_mask:0xf bank_mask:0xf
	s_and_saveexec_b64 s[0:1], s[12:13]
	s_cbranch_execz .LBB0_207
	s_waitcnt lgkmcnt(0)
	v_cvt_pk_bf16_f32 v139, v122, v134
	v_or_b32_e32 v134, v138, v164
	v_lshl_add_u64 v[140:141], v[134:135], 4, v[132:133]
	global_store_dword v[140:141], v139, off
; DI size_t vf_off(int h, int nblk, int krow, int d) { const int kk = krow & 31; return (((((size_t)h * nblk + (krow >> 5)) * 2 + (d >> 5)) * 2 + (kk >> 4)) * 64 + ((kk >> 2) & 1) * 32 + (d & 31)) * 8 + 4 * ((kk >> 3) & 1) + (kk & 3); }
;     DI void operator()(const AccT& acc, const Unit& u, int wr, int wc, int fr, int fq, LAS unsigned char*) const {
;     ...
;                     } else {
;                         bf16_t* vp = (bf16_t*)(ws + (isA ? WS_VTA : WS_VTB));
; #pragma unroll
;                         for (int bj = 0; bj < 2; ++bj)
; #pragma unroll
;                             for (int n = 0; n < 2; ++n)
; #pragma unroll
;                                 for (int j = 0; j < 4; ++j) {
;                                     const float mine = v[bj][n][j], oth = __shfl_xor(mine, 1);
;                                     if (!(fr & 1)) *(unsigned*)(vp + vf_off(h, krows >> 5, krow, 32 * bj + 16 * n + 4 * fq + j)) = pk2(mine, oth);
;                                 }
.LBB0_207:
	s_or_b64 exec, exec, s[0:1]
	s_waitcnt lgkmcnt(0)
	v_mov_b32_dpp v134, v123 quad_perm:[1,0,3,2] row_mask:0xf bank_mask:0xf
	s_and_saveexec_b64 s[0:1], s[12:13]
	s_cbranch_execz .LBB0_209
	s_waitcnt lgkmcnt(0)
	v_cvt_pk_bf16_f32 v140, v123, v134
	v_or_b32_e32 v134, v138, v166
	v_lshl_add_u64 v[138:139], v[134:135], 4, v[132:133]
	global_store_dword v[138:139], v140, off
.LBB0_209:
	s_or_b64 exec, exec, s[0:1]
	s_waitcnt lgkmcnt(0)
	v_mov_b32_dpp v134, v116 quad_perm:[1,0,3,2] row_mask:0xf bank_mask:0xf
	v_or_b32_e32 v137, 0xc0, v137
	s_and_saveexec_b64 s[0:1], s[12:13]
	s_cbranch_execz .LBB0_211
	s_waitcnt lgkmcnt(0)
	v_cvt_pk_bf16_f32 v140, v116, v134
	v_or_b32_e32 v134, v137, v152
	v_lshl_add_u64 v[138:139], v[134:135], 4, v[132:133]
	global_store_dword v[138:139], v140, off
.LBB0_211:
	s_or_b64 exec, exec, s[0:1]
	s_waitcnt lgkmcnt(0)
	v_mov_b32_dpp v134, v117 quad_perm:[1,0,3,2] row_mask:0xf bank_mask:0xf
	s_and_saveexec_b64 s[0:1], s[12:13]
	s_cbranch_execz .LBB0_213
	s_waitcnt lgkmcnt(0)
	v_cvt_pk_bf16_f32 v140, v117, v134
	v_or_b32_e32 v134, v137, v154
	v_lshl_add_u64 v[138:139], v[134:135], 4, v[132:133]
	global_store_dword v[138:139], v140, off
.LBB0_213:
	s_or_b64 exec, exec, s[0:1]
	s_waitcnt lgkmcnt(0)
	v_mov_b32_dpp v134, v118 quad_perm:[1,0,3,2] row_mask:0xf bank_mask:0xf
	s_and_saveexec_b64 s[0:1], s[12:13]
	s_cbranch_execz .LBB0_215
	s_waitcnt lgkmcnt(0)
	v_cvt_pk_bf16_f32 v140, v118, v134
	v_or_b32_e32 v134, v137, v156
	v_lshl_add_u64 v[138:139], v[134:135], 4, v[132:133]
	global_store_dword v[138:139], v140, off
.LBB0_215:
	s_or_b64 exec, exec, s[0:1]
	s_waitcnt lgkmcnt(0)
	v_mov_b32_dpp v134, v119 quad_perm:[1,0,3,2] row_mask:0xf bank_mask:0xf
	s_and_saveexec_b64 s[0:1], s[12:13]
	s_cbranch_execz .LBB0_217
	s_waitcnt lgkmcnt(0)
	v_cvt_pk_bf16_f32 v140, v119, v134
	v_or_b32_e32 v134, v137, v158
	v_lshl_add_u64 v[138:139], v[134:135], 4, v[132:133]
	global_store_dword v[138:139], v140, off
.LBB0_217:
	s_or_b64 exec, exec, s[0:1]
	s_waitcnt lgkmcnt(0)
	v_mov_b32_dpp v134, v112 quad_perm:[1,0,3,2] row_mask:0xf bank_mask:0xf
	s_and_saveexec_b64 s[0:1], s[12:13]
	s_cbranch_execz .LBB0_219
	s_waitcnt lgkmcnt(0)
	v_cvt_pk_bf16_f32 v140, v112, v134
	v_or_b32_e32 v134, v137, v160
	v_lshl_add_u64 v[138:139], v[134:135], 4, v[132:133]
	global_store_dword v[138:139], v140, off
.LBB0_219:
	s_or_b64 exec, exec, s[0:1]
	s_waitcnt lgkmcnt(0)
	v_mov_b32_dpp v134, v113 quad_perm:[1,0,3,2] row_mask:0xf bank_mask:0xf
	s_and_saveexec_b64 s[0:1], s[12:13]
	s_cbranch_execz .LBB0_221
	s_waitcnt lgkmcnt(0)
	v_cvt_pk_bf16_f32 v140, v113, v134
	v_or_b32_e32 v134, v137, v162
	v_lshl_add_u64 v[138:139], v[134:135], 4, v[132:133]
	global_store_dword v[138:139], v140, off
.LBB0_221:
	s_or_b64 exec, exec, s[0:1]
	s_waitcnt lgkmcnt(0)
	v_mov_b32_dpp v134, v114 quad_perm:[1,0,3,2] row_mask:0xf bank_mask:0xf
	s_and_saveexec_b64 s[0:1], s[12:13]
	s_cbranch_execz .LBB0_223
	s_waitcnt lgkmcnt(0)
	v_cvt_pk_bf16_f32 v140, v114, v134
	v_or_b32_e32 v134, v137, v164
	v_lshl_add_u64 v[138:139], v[134:135], 4, v[132:133]
	global_store_dword v[138:139], v140, off
.LBB0_223:
	s_or_b64 exec, exec, s[0:1]
	s_waitcnt lgkmcnt(0)
	v_mov_b32_dpp v134, v115 quad_perm:[1,0,3,2] row_mask:0xf bank_mask:0xf
	s_and_saveexec_b64 s[0:1], s[12:13]
	s_cbranch_execz .LBB0_225
	s_waitcnt lgkmcnt(0)
	v_cvt_pk_bf16_f32 v136, v115, v134
	v_or_b32_e32 v134, v137, v166
	v_lshl_add_u64 v[132:133], v[134:135], 4, v[132:133]
	global_store_dword v[132:133], v136, off

;     DI void operator()(const AccT& acc, const Unit& u, int wr, int wc, int fr, int fq, LAS unsigned char*) const {
;     ...
;                 if (donorm) {
;                     float ss = 0.f;
; #pragma unroll
;                     for (int bj = 0; bj < 2; ++bj)
; #pragma unroll
;                         for (int n = 0; n < 2; ++n) ss += (v[bj][n][0] * v[bj][n][0] + v[bj][n][1] * v[bj][n][1]) + (v[bj][n][2] * v[bj][n][2] + v[bj][n][3] * v[bj][n][3]);
;                     ss += __shfl_xor(ss, 16); ss += __shfl_xor(ss, 32);
;                     const float rs = rsqrtf(ss * (1.f / 64.f) + EPS);
; #pragma unroll
;                     for (int bj = 0; bj < 2; ++bj)
; #pragma unroll
;                         for (int n = 0; n < 2; ++n) v[bj][n] = v[bj][n] * rs * gv[bj][n];
;                 }
.LBB0_230:
	v_pk_mul_f32 v[112:113], v[110:111], v[110:111]
	v_pk_mul_f32 v[114:115], v[108:109], v[108:109]
	s_nop 0
	v_pk_mov_b32 v[116:117], v[114:115], v[112:113] op_sel:[1,0]
	v_mov_b32_e32 v115, v113
	v_pk_add_f32 v[112:113], v[116:117], v[114:115]
	v_pk_mul_f32 v[114:115], v[106:107], v[106:107]
	v_pk_add_f32 v[112:113], v[112:113], v[112:113] op_sel_hi:[0,1]
	v_pk_mul_f32 v[116:117], v[104:105], v[104:105]
	v_mul_f32_e32 v112, v100, v100
	v_pk_mov_b32 v[118:119], v[116:117], v[114:115] op_sel:[1,0]
	v_mov_b32_e32 v117, v115
	v_pk_add_f32 v[114:115], v[118:119], v[116:117]
	v_pk_fma_f32 v[116:117], v[100:101], v[100:101], v[112:113] op_sel_hi:[1,1,0]
	v_mul_f32_e32 v112, v102, v102
	v_pk_add_f32 v[114:115], v[114:115], v[114:115] op_sel_hi:[0,1]
	v_pk_fma_f32 v[118:119], v[102:103], v[102:103], v[112:113] op_sel_hi:[1,1,0]
	v_mul_f32_e32 v116, v96, v96
	v_mul_f32_e32 v118, v97, v97
	v_mul_f32_e32 v114, v98, v98
	v_mul_f32_e32 v112, v99, v99
	v_pk_add_f32 v[116:117], v[116:117], v[118:119]
	v_pk_add_f32 v[112:113], v[114:115], v[112:113]
	v_and_b32_e32 v114, 64, v198
	v_pk_add_f32 v[112:113], v[116:117], v[112:113]
	v_add_u32_e32 v114, 64, v114
	v_add_f32_e32 v112, v112, v113
	v_mov_b32_e32 v113, v112
	s_nop 1
	v_permlane16_swap_b32_e32 v113, v112
	v_add_f32_e32 v112, v112, v113
	v_mov_b32_e32 v113, v112
	s_nop 1
	v_permlane32_swap_b32_e32 v113, v112
	s_waitcnt lgkmcnt(0)
	v_add_f32_e32 v112, v112, v113
	v_fmamk_f32 v112, v112, 0x3c800000, v195
	v_mul_f32_e32 v113, 0x4b800000, v112
	v_cmp_gt_f32_e32 vcc, s78, v112
	s_nop 1
	v_cndmask_b32_e32 v112, v112, v113, vcc
	v_rsq_f32_e32 v112, v112
	s_nop 0
	v_mul_f32_e32 v113, 0x45800000, v112
	v_cndmask_b32_e32 v112, v112, v113, vcc
	v_pk_mul_f32 v[108:109], v[108:109], v[112:113] op_sel_hi:[1,0]
	v_pk_mul_f32 v[110:111], v[110:111], v[112:113] op_sel_hi:[1,0]
	v_pk_mul_f32 v[104:105], v[104:105], v[112:113] op_sel_hi:[1,0]
	v_pk_mul_f32 v[106:107], v[106:107], v[112:113] op_sel_hi:[1,0]
	v_pk_mul_f32 v[100:101], v[100:101], v[112:113] op_sel_hi:[1,0]
	v_pk_mul_f32 v[102:103], v[102:103], v[112:113] op_sel_hi:[1,0]
	v_pk_mul_f32 v[96:97], v[96:97], v[112:113] op_sel_hi:[1,0]
	v_pk_mul_f32 v[98:99], v[98:99], v[112:113] op_sel_hi:[1,0]
	s_waitcnt vmcnt(0)
	v_pk_mul_f32 v[110:111], v[54:55], v[110:111]
	v_pk_mul_f32 v[108:109], v[52:53], v[108:109]
	v_pk_mul_f32 v[106:107], v[50:51], v[106:107]
	v_pk_mul_f32 v[104:105], v[48:49], v[104:105]
	v_pk_mul_f32 v[102:103], v[62:63], v[102:103]
	v_pk_mul_f32 v[100:101], v[60:61], v[100:101]
	v_pk_mul_f32 v[98:99], v[58:59], v[98:99]
	v_pk_mul_f32 v[96:97], v[56:57], v[96:97]
	s_and_b64 vcc, exec, s[8:9]
	v_or_b32_e32 v112, 32, v182
	s_cbranch_vccz .LBB0_509

; DI u32x2 pk4(f32x4 v) { u32x2 r; r.x = pk2(v[0], v[1]); r.y = pk2(v[2], v[3]); return r; }
;     DI void operator()(const AccT& acc, const Unit& u, int wr, int wc, int fr, int fq, LAS unsigned char*) const {
;     ...
;                     const bool isA = (kind == 1 || kind == 2), isK = (kind == 1 || kind == 4);
;                     const int srow = row - SEQ;
;                     const int band = isA ? 576 : 192, past = isA ? 512 : 128, nh = isA ? 8 : 2;
;                     const int krow = row < SEQ ? row : SEQ + (srow >> 6) * band + past + (srow & 63);
;                     const int krows = isA ? KA_ROWS : KB_ROWS;
;                     float* op = nullptr;
;                     size_t ooff = 0; bool has_o = false;
;                     if (row >= SEQ) { ooff = (isA ? (isK ? OFF_AKS : OFF_AVS) : (isK ? OFF_BKS : OFF_BVS)) + ((size_t)srow * nh + h) * 64; has_o = true; }
;                     else if (row >= SEQ - past) { ooff = (isA ? (isK ? OFF_AKP : OFF_AVP) : (isK ? OFF_BKP : OFF_BVP)) + ((size_t)(row - (SEQ - past)) * nh + h) * 64; has_o = true; }
;                     op = out + ooff;
;                     if (has_o) {
; #pragma unroll
;                         for (int bj = 0; bj < 2; ++bj)
; #pragma unroll
;                             for (int n = 0; n < 2; ++n) *(f32x4*)(op + 32 * bj + 16 * n + 4 * fq) = v[bj][n];
;                     }
;                     if (isK) {
;                         bf16_t* kp = (bf16_t*)(ws + (isA ? WS_KA : WS_KB));
; #pragma unroll
;                         for (int bj = 0; bj < 2; ++bj)
; #pragma unroll
;                             for (int n = 0; n < 2; ++n) *(u32x2*)(kp + kf_off(h, krows >> 5, krow, 32 * bj + 16 * n + 4 * fq)) = pk4(v[bj][n]);
;                     } else {
;                         bf16_t* vp = (bf16_t*)(ws + (isA ? WS_VTA : WS_VTB));
; #pragma unroll
;                         for (int bj = 0; bj < 2; ++bj)
; #pragma unroll
;                             for (int n = 0; n < 2; ++n)
; #pragma unroll
;                                 for (int j = 0; j < 4; ++j) {
;                                     const float mine = v[bj][n][j], oth = __shfl_xor(mine, 1);
;                                     if (!(fr & 1)) *(unsigned*)(vp + vf_off(h, krows >> 5, krow, 32 * bj + 16 * n + 4 * fq + j)) = pk2(mine, oth);
;                                 }
.LBB0_238:
	s_or_b64 exec, exec, s[0:1]
	v_lshrrev_b32_e32 v113, 6, v113
	v_or_b32_e32 v114, s90, v192
	v_mad_u64_u32 v[114:115], s[0:1], s31, v113, v[114:115]
	v_cmp_gt_i32_e32 vcc, s68, v112
	s_mov_b64 s[0:1], -1
	s_nop 0
	v_cndmask_b32_e32 v113, v114, v112, vcc
	v_ashrrev_i32_e32 v114, 5, v113
	s_andn2_b64 vcc, exec, s[50:51]
	v_ashrrev_i32_e32 v115, 31, v114
	s_cbranch_vccnz .LBB0_272
	v_and_b32_e32 v117, 64, v198
	v_xor_b32_e32 v116, 1, v198
	v_add_u32_e32 v117, 64, v117
	v_cmp_lt_i32_e32 vcc, v116, v117
	s_add_u32 s0, s36, s91
	s_addc_u32 s1, s37, 0
	v_cndmask_b32_e32 v116, v198, v116, vcc
	v_lshlrev_b32_e32 v120, 2, v116
	v_lshlrev_b32_e32 v116, 3, v113
	v_and_b32_e32 v122, 3, v113
	v_and_b32_e32 v150, 8, v113
	v_and_b32_e32 v121, 32, v116
	v_lshl_add_u64 v[116:117], s[0:1], 0, v[150:151]
	v_lshlrev_b32_e32 v150, 1, v122
	v_mov_b32_dpp v122, v108 quad_perm:[1,0,3,2] row_mask:0xf bank_mask:0xf
	v_lshl_add_u64 v[118:119], s[46:47], 0, v[114:115]
	v_lshlrev_b32_e32 v123, 2, v113
	v_lshlrev_b64 v[118:119], 8, v[118:119]
	v_and_b32_e32 v123, 64, v123
	v_lshl_add_u64 v[116:117], v[116:117], 0, v[150:151]
	v_or3_b32 v121, v118, v123, v121
	s_and_saveexec_b64 s[0:1], s[12:13]
	s_cbranch_execz .LBB0_241
	v_or_b32_e32 v118, v121, v152
	s_waitcnt lgkmcnt(0)
	v_cvt_pk_bf16_f32 v124, v108, v122
	v_lshl_add_u64 v[122:123], v[118:119], 4, v[116:117]
	global_store_dword v[122:123], v124, off
.LBB0_241:
	s_or_b64 exec, exec, s[0:1]
	v_mov_b32_dpp v118, v109 quad_perm:[1,0,3,2] row_mask:0xf bank_mask:0xf
	s_and_saveexec_b64 s[0:1], s[12:13]
	s_cbranch_execz .LBB0_243
	s_waitcnt lgkmcnt(0)
	v_cvt_pk_bf16_f32 v124, v109, v118
	v_or_b32_e32 v118, v121, v154
	v_lshl_add_u64 v[122:123], v[118:119], 4, v[116:117]
	global_store_dword v[122:123], v124, off
.LBB0_243:
	s_or_b64 exec, exec, s[0:1]
	s_waitcnt lgkmcnt(0)
	v_mov_b32_dpp v118, v110 quad_perm:[1,0,3,2] row_mask:0xf bank_mask:0xf
	s_and_saveexec_b64 s[0:1], s[12:13]
	s_cbranch_execz .LBB0_245
	s_waitcnt lgkmcnt(0)
	v_cvt_pk_bf16_f32 v124, v110, v118
	v_or_b32_e32 v118, v121, v156
	v_lshl_add_u64 v[122:123], v[118:119], 4, v[116:117]
	global_store_dword v[122:123], v124, off
.LBB0_245:
	s_or_b64 exec, exec, s[0:1]
	s_waitcnt lgkmcnt(0)
	v_mov_b32_dpp v118, v111 quad_perm:[1,0,3,2] row_mask:0xf bank_mask:0xf
	s_and_saveexec_b64 s[0:1], s[12:13]
	s_cbranch_execz .LBB0_247
	s_waitcnt lgkmcnt(0)
	v_cvt_pk_bf16_f32 v124, v111, v118
	v_or_b32_e32 v118, v121, v158
	v_lshl_add_u64 v[122:123], v[118:119], 4, v[116:117]
	global_store_dword v[122:123], v124, off
.LBB0_247:
	s_or_b64 exec, exec, s[0:1]
	s_waitcnt lgkmcnt(0)
	v_mov_b32_dpp v118, v104 quad_perm:[1,0,3,2] row_mask:0xf bank_mask:0xf
	s_and_saveexec_b64 s[0:1], s[12:13]
	s_cbranch_execz .LBB0_249
	s_waitcnt lgkmcnt(0)
	v_cvt_pk_bf16_f32 v124, v104, v118
	v_or_b32_e32 v118, v121, v160
	v_lshl_add_u64 v[122:123], v[118:119], 4, v[116:117]
	global_store_dword v[122:123], v124, off
.LBB0_249:
	s_or_b64 exec, exec, s[0:1]
	s_waitcnt lgkmcnt(0)
	v_mov_b32_dpp v118, v105 quad_perm:[1,0,3,2] row_mask:0xf bank_mask:0xf
	s_and_saveexec_b64 s[0:1], s[12:13]
	s_cbranch_execz .LBB0_251
	s_waitcnt lgkmcnt(0)
	v_cvt_pk_bf16_f32 v124, v105, v118
	v_or_b32_e32 v118, v121, v162
	v_lshl_add_u64 v[122:123], v[118:119], 4, v[116:117]
	global_store_dword v[122:123], v124, off
.LBB0_251:
	s_or_b64 exec, exec, s[0:1]
	s_waitcnt lgkmcnt(0)
	v_mov_b32_dpp v118, v106 quad_perm:[1,0,3,2] row_mask:0xf bank_mask:0xf
	s_and_saveexec_b64 s[0:1], s[12:13]
	s_cbranch_execz .LBB0_253
	s_waitcnt lgkmcnt(0)
	v_cvt_pk_bf16_f32 v124, v106, v118
	v_or_b32_e32 v118, v121, v164
	v_lshl_add_u64 v[122:123], v[118:119], 4, v[116:117]
	global_store_dword v[122:123], v124, off
; DI size_t vf_off(int h, int nblk, int krow, int d) { const int kk = krow & 31; return (((((size_t)h * nblk + (krow >> 5)) * 2 + (d >> 5)) * 2 + (kk >> 4)) * 64 + ((kk >> 2) & 1) * 32 + (d & 31)) * 8 + 4 * ((kk >> 3) & 1) + (kk & 3); }
;     DI void operator()(const AccT& acc, const Unit& u, int wr, int wc, int fr, int fq, LAS unsigned char*) const {
;     ...
;                     } else {
;                         bf16_t* vp = (bf16_t*)(ws + (isA ? WS_VTA : WS_VTB));
; #pragma unroll
;                         for (int bj = 0; bj < 2; ++bj)
; #pragma unroll
;                             for (int n = 0; n < 2; ++n)
; #pragma unroll
;                                 for (int j = 0; j < 4; ++j) {
;                                     const float mine = v[bj][n][j], oth = __shfl_xor(mine, 1);
;                                     if (!(fr & 1)) *(unsigned*)(vp + vf_off(h, krows >> 5, krow, 32 * bj + 16 * n + 4 * fq + j)) = pk2(mine, oth);
;                                 }
.LBB0_253:
	s_or_b64 exec, exec, s[0:1]
	s_waitcnt lgkmcnt(0)
	v_mov_b32_dpp v118, v107 quad_perm:[1,0,3,2] row_mask:0xf bank_mask:0xf
	s_and_saveexec_b64 s[0:1], s[12:13]
	s_cbranch_execz .LBB0_255
	s_waitcnt lgkmcnt(0)
	v_cvt_pk_bf16_f32 v124, v107, v118
	v_or_b32_e32 v118, v121, v166
	v_lshl_add_u64 v[122:123], v[118:119], 4, v[116:117]
	global_store_dword v[122:123], v124, off
.LBB0_255:
	s_or_b64 exec, exec, s[0:1]
	s_waitcnt lgkmcnt(0)
	v_mov_b32_dpp v118, v100 quad_perm:[1,0,3,2] row_mask:0xf bank_mask:0xf
	v_or_b32_e32 v121, 0x80, v121
	s_and_saveexec_b64 s[0:1], s[12:13]
	s_cbranch_execz .LBB0_257
	s_waitcnt lgkmcnt(0)
	v_cvt_pk_bf16_f32 v124, v100, v118
	v_or_b32_e32 v118, v121, v152
	v_lshl_add_u64 v[122:123], v[118:119], 4, v[116:117]
	global_store_dword v[122:123], v124, off
.LBB0_257:
	s_or_b64 exec, exec, s[0:1]
	s_waitcnt lgkmcnt(0)
	v_mov_b32_dpp v118, v101 quad_perm:[1,0,3,2] row_mask:0xf bank_mask:0xf
	s_and_saveexec_b64 s[0:1], s[12:13]
	s_cbranch_execz .LBB0_259
	s_waitcnt lgkmcnt(0)
	v_cvt_pk_bf16_f32 v124, v101, v118
	v_or_b32_e32 v118, v121, v154
	v_lshl_add_u64 v[122:123], v[118:119], 4, v[116:117]
	global_store_dword v[122:123], v124, off
.LBB0_259:
	s_or_b64 exec, exec, s[0:1]
	s_waitcnt lgkmcnt(0)
	v_mov_b32_dpp v118, v102 quad_perm:[1,0,3,2] row_mask:0xf bank_mask:0xf
	s_and_saveexec_b64 s[0:1], s[12:13]
	s_cbranch_execz .LBB0_261
	s_waitcnt lgkmcnt(0)
	v_cvt_pk_bf16_f32 v124, v102, v118
	v_or_b32_e32 v118, v121, v156
	v_lshl_add_u64 v[122:123], v[118:119], 4, v[116:117]
	global_store_dword v[122:123], v124, off
.LBB0_261:
	s_or_b64 exec, exec, s[0:1]
	s_waitcnt lgkmcnt(0)
	v_mov_b32_dpp v118, v103 quad_perm:[1,0,3,2] row_mask:0xf bank_mask:0xf
	s_and_saveexec_b64 s[0:1], s[12:13]
	s_cbranch_execz .LBB0_263
	s_waitcnt lgkmcnt(0)
	v_cvt_pk_bf16_f32 v124, v103, v118
	v_or_b32_e32 v118, v121, v158
	v_lshl_add_u64 v[122:123], v[118:119], 4, v[116:117]
	global_store_dword v[122:123], v124, off
.LBB0_263:
	s_or_b64 exec, exec, s[0:1]
	s_waitcnt lgkmcnt(0)
	v_mov_b32_dpp v118, v96 quad_perm:[1,0,3,2] row_mask:0xf bank_mask:0xf
	s_and_saveexec_b64 s[0:1], s[12:13]
	s_cbranch_execz .LBB0_265
	s_waitcnt lgkmcnt(0)
	v_cvt_pk_bf16_f32 v124, v96, v118
	v_or_b32_e32 v118, v121, v160
	v_lshl_add_u64 v[122:123], v[118:119], 4, v[116:117]
	global_store_dword v[122:123], v124, off
.LBB0_265:
	s_or_b64 exec, exec, s[0:1]
	s_waitcnt lgkmcnt(0)
	v_mov_b32_dpp v118, v97 quad_perm:[1,0,3,2] row_mask:0xf bank_mask:0xf
	s_and_saveexec_b64 s[0:1], s[12:13]
	s_cbranch_execz .LBB0_267
	s_waitcnt lgkmcnt(0)
	v_cvt_pk_bf16_f32 v124, v97, v118
	v_or_b32_e32 v118, v121, v162
	v_lshl_add_u64 v[122:123], v[118:119], 4, v[116:117]
	global_store_dword v[122:123], v124, off
.LBB0_267:
	s_or_b64 exec, exec, s[0:1]
	s_waitcnt lgkmcnt(0)
	v_mov_b32_dpp v118, v98 quad_perm:[1,0,3,2] row_mask:0xf bank_mask:0xf
	s_and_saveexec_b64 s[0:1], s[12:13]
	s_cbranch_execz .LBB0_269
	s_waitcnt lgkmcnt(0)
	v_cvt_pk_bf16_f32 v124, v98, v118
	v_or_b32_e32 v118, v121, v164
	v_lshl_add_u64 v[122:123], v[118:119], 4, v[116:117]
	global_store_dword v[122:123], v124, off
.LBB0_269:
	s_or_b64 exec, exec, s[0:1]
	s_waitcnt lgkmcnt(0)
	v_mov_b32_dpp v118, v99 quad_perm:[1,0,3,2] row_mask:0xf bank_mask:0xf
	s_and_saveexec_b64 s[0:1], s[12:13]
	s_cbranch_execz .LBB0_271
	s_waitcnt lgkmcnt(0)
	v_cvt_pk_bf16_f32 v120, v99, v118
	v_or_b32_e32 v118, v121, v166
	v_lshl_add_u64 v[116:117], v[118:119], 4, v[116:117]
	global_store_dword v[116:117], v120, off

;     DI void operator()(const AccT& acc, const Unit& u, int wr, int wc, int fr, int fq, LAS unsigned char*) const {
;     ...
;                 if (donorm) {
;                     float ss = 0.f;
; #pragma unroll
;                     for (int bj = 0; bj < 2; ++bj)
; #pragma unroll
;                         for (int n = 0; n < 2; ++n) ss += (v[bj][n][0] * v[bj][n][0] + v[bj][n][1] * v[bj][n][1]) + (v[bj][n][2] * v[bj][n][2] + v[bj][n][3] * v[bj][n][3]);
;                     ss += __shfl_xor(ss, 16); ss += __shfl_xor(ss, 32);
;                     const float rs = rsqrtf(ss * (1.f / 64.f) + EPS);
; #pragma unroll
;                     for (int bj = 0; bj < 2; ++bj)
; #pragma unroll
;                         for (int n = 0; n < 2; ++n) v[bj][n] = v[bj][n] * rs * gv[bj][n];
;                 }
.LBB0_276:
	v_pk_mul_f32 v[96:97], v[94:95], v[94:95]
	v_pk_mul_f32 v[98:99], v[92:93], v[92:93]
	s_nop 0
	v_pk_mov_b32 v[100:101], v[98:99], v[96:97] op_sel:[1,0]
	v_mov_b32_e32 v99, v97
	v_pk_add_f32 v[96:97], v[100:101], v[98:99]
	v_pk_mul_f32 v[98:99], v[90:91], v[90:91]
	v_pk_add_f32 v[96:97], v[96:97], v[96:97] op_sel_hi:[0,1]
	v_pk_mul_f32 v[100:101], v[88:89], v[88:89]
	v_mul_f32_e32 v96, v84, v84
	v_pk_mov_b32 v[102:103], v[100:101], v[98:99] op_sel:[1,0]
	v_mov_b32_e32 v101, v99
	v_pk_add_f32 v[98:99], v[102:103], v[100:101]
	v_pk_fma_f32 v[100:101], v[84:85], v[84:85], v[96:97] op_sel_hi:[1,1,0]
	v_mul_f32_e32 v96, v86, v86
	v_pk_add_f32 v[98:99], v[98:99], v[98:99] op_sel_hi:[0,1]
	v_pk_fma_f32 v[102:103], v[86:87], v[86:87], v[96:97] op_sel_hi:[1,1,0]
	v_mul_f32_e32 v100, v80, v80
	v_mul_f32_e32 v102, v81, v81
	v_mul_f32_e32 v98, v82, v82
	v_mul_f32_e32 v96, v83, v83
	v_pk_add_f32 v[100:101], v[100:101], v[102:103]
	v_pk_add_f32 v[96:97], v[98:99], v[96:97]
	v_and_b32_e32 v98, 64, v198
	v_pk_add_f32 v[96:97], v[100:101], v[96:97]
	v_add_u32_e32 v98, 64, v98
	v_add_f32_e32 v96, v96, v97
	v_mov_b32_e32 v97, v96
	s_nop 1
	v_permlane16_swap_b32_e32 v97, v96
	v_add_f32_e32 v96, v96, v97
	v_mov_b32_e32 v97, v96
	s_nop 1
	v_permlane32_swap_b32_e32 v97, v96
	s_waitcnt lgkmcnt(0)
	v_add_f32_e32 v96, v96, v97
	v_fmamk_f32 v96, v96, 0x3c800000, v195
	v_mul_f32_e32 v97, 0x4b800000, v96
	v_cmp_gt_f32_e32 vcc, s78, v96
	s_nop 1
	v_cndmask_b32_e32 v96, v96, v97, vcc
	v_rsq_f32_e32 v96, v96
	s_nop 0
	v_mul_f32_e32 v97, 0x45800000, v96
	v_cndmask_b32_e32 v96, v96, v97, vcc
	v_pk_mul_f32 v[92:93], v[92:93], v[96:97] op_sel_hi:[1,0]
	v_pk_mul_f32 v[94:95], v[94:95], v[96:97] op_sel_hi:[1,0]
	v_pk_mul_f32 v[88:89], v[88:89], v[96:97] op_sel_hi:[1,0]
	v_pk_mul_f32 v[90:91], v[90:91], v[96:97] op_sel_hi:[1,0]
	v_pk_mul_f32 v[84:85], v[84:85], v[96:97] op_sel_hi:[1,0]
	v_pk_mul_f32 v[86:87], v[86:87], v[96:97] op_sel_hi:[1,0]
	v_pk_mul_f32 v[80:81], v[80:81], v[96:97] op_sel_hi:[1,0]
	v_pk_mul_f32 v[82:83], v[82:83], v[96:97] op_sel_hi:[1,0]
	s_waitcnt vmcnt(0)
	v_pk_mul_f32 v[94:95], v[54:55], v[94:95]
	v_pk_mul_f32 v[92:93], v[52:53], v[92:93]
	v_pk_mul_f32 v[90:91], v[50:51], v[90:91]
	v_pk_mul_f32 v[88:89], v[48:49], v[88:89]
	v_pk_mul_f32 v[86:87], v[62:63], v[86:87]
	v_pk_mul_f32 v[84:85], v[60:61], v[84:85]
	v_pk_mul_f32 v[82:83], v[58:59], v[82:83]
	v_pk_mul_f32 v[80:81], v[56:57], v[80:81]
	s_and_b64 vcc, exec, s[8:9]
	v_or_b32_e32 v96, 48, v182
	s_cbranch_vccz .LBB0_513

; DI u32x2 pk4(f32x4 v) { u32x2 r; r.x = pk2(v[0], v[1]); r.y = pk2(v[2], v[3]); return r; }
;     DI void operator()(const AccT& acc, const Unit& u, int wr, int wc, int fr, int fq, LAS unsigned char*) const {
;     ...
;                     const bool isA = (kind == 1 || kind == 2), isK = (kind == 1 || kind == 4);
;                     const int srow = row - SEQ;
;                     const int band = isA ? 576 : 192, past = isA ? 512 : 128, nh = isA ? 8 : 2;
;                     const int krow = row < SEQ ? row : SEQ + (srow >> 6) * band + past + (srow & 63);
;                     const int krows = isA ? KA_ROWS : KB_ROWS;
;                     float* op = nullptr;
;                     size_t ooff = 0; bool has_o = false;
;                     if (row >= SEQ) { ooff = (isA ? (isK ? OFF_AKS : OFF_AVS) : (isK ? OFF_BKS : OFF_BVS)) + ((size_t)srow * nh + h) * 64; has_o = true; }
;                     else if (row >= SEQ - past) { ooff = (isA ? (isK ? OFF_AKP : OFF_AVP) : (isK ? OFF_BKP : OFF_BVP)) + ((size_t)(row - (SEQ - past)) * nh + h) * 64; has_o = true; }
;                     op = out + ooff;
;                     if (has_o) {
; #pragma unroll
;                         for (int bj = 0; bj < 2; ++bj)
; #pragma unroll
;                             for (int n = 0; n < 2; ++n) *(f32x4*)(op + 32 * bj + 16 * n + 4 * fq) = v[bj][n];
;                     }
;                     if (isK) {
;                         bf16_t* kp = (bf16_t*)(ws + (isA ? WS_KA : WS_KB));
; #pragma unroll
;                         for (int bj = 0; bj < 2; ++bj)
; #pragma unroll
;                             for (int n = 0; n < 2; ++n) *(u32x2*)(kp + kf_off(h, krows >> 5, krow, 32 * bj + 16 * n + 4 * fq)) = pk4(v[bj][n]);
;                     } else {
;                         bf16_t* vp = (bf16_t*)(ws + (isA ? WS_VTA : WS_VTB));
; #pragma unroll
;                         for (int bj = 0; bj < 2; ++bj)
; #pragma unroll
;                             for (int n = 0; n < 2; ++n)
; #pragma unroll
;                                 for (int j = 0; j < 4; ++j) {
;                                     const float mine = v[bj][n][j], oth = __shfl_xor(mine, 1);
;                                     if (!(fr & 1)) *(unsigned*)(vp + vf_off(h, krows >> 5, krow, 32 * bj + 16 * n + 4 * fq + j)) = pk2(mine, oth);
;                                 }
.LBB0_284:
	s_or_b64 exec, exec, s[0:1]
	v_lshrrev_b32_e32 v97, 6, v97
	v_or_b32_e32 v98, s90, v193
	v_mad_u64_u32 v[98:99], s[0:1], s31, v97, v[98:99]
	v_cmp_gt_i32_e32 vcc, s68, v96
	s_mov_b64 s[0:1], -1
	s_nop 0
	v_cndmask_b32_e32 v97, v98, v96, vcc
	v_ashrrev_i32_e32 v98, 5, v97
	s_andn2_b64 vcc, exec, s[50:51]
	v_ashrrev_i32_e32 v99, 31, v98
	s_cbranch_vccnz .LBB0_318
	v_and_b32_e32 v101, 64, v198
	v_xor_b32_e32 v100, 1, v198
	v_add_u32_e32 v101, 64, v101
	v_cmp_lt_i32_e32 vcc, v100, v101
	s_add_u32 s0, s36, s91
	v_lshl_add_u64 v[102:103], s[46:47], 0, v[98:99]
	v_cndmask_b32_e32 v100, v198, v100, vcc
	v_lshlrev_b32_e32 v104, 2, v100
	v_mov_b32_dpp v107, v92 quad_perm:[1,0,3,2] row_mask:0xf bank_mask:0xf
	s_addc_u32 s1, s37, 0
	v_lshlrev_b32_e32 v105, 3, v97
	v_and_b32_e32 v106, 3, v97
	v_and_b32_e32 v150, 8, v97
	v_lshlrev_b64 v[102:103], 8, v[102:103]
	v_lshl_add_u64 v[100:101], s[0:1], 0, v[150:151]
	v_lshlrev_b32_e32 v150, 1, v106
	v_and_or_b32 v105, v105, 32, v102
	v_lshl_add_u64 v[100:101], v[100:101], 0, v[150:151]
	v_or_b32_e32 v106, 64, v105
	s_and_saveexec_b64 s[0:1], s[12:13]
	s_cbranch_execz .LBB0_287
	v_or_b32_e32 v102, v106, v152
	s_waitcnt lgkmcnt(0)
	v_cvt_pk_bf16_f32 v107, v92, v107
	v_lshl_add_u64 v[108:109], v[102:103], 4, v[100:101]
	global_store_dword v[108:109], v107, off
.LBB0_287:
	s_or_b64 exec, exec, s[0:1]
	v_mov_b32_dpp v102, v93 quad_perm:[1,0,3,2] row_mask:0xf bank_mask:0xf
	s_and_saveexec_b64 s[0:1], s[12:13]
	s_cbranch_execz .LBB0_289
	s_waitcnt lgkmcnt(0)
	v_cvt_pk_bf16_f32 v107, v93, v102
	v_or_b32_e32 v102, v106, v154
	v_lshl_add_u64 v[108:109], v[102:103], 4, v[100:101]
	global_store_dword v[108:109], v107, off
.LBB0_289:
	s_or_b64 exec, exec, s[0:1]
	s_waitcnt lgkmcnt(0)
	v_mov_b32_dpp v102, v94 quad_perm:[1,0,3,2] row_mask:0xf bank_mask:0xf
	s_and_saveexec_b64 s[0:1], s[12:13]
	s_cbranch_execz .LBB0_291
	s_waitcnt lgkmcnt(0)
	v_cvt_pk_bf16_f32 v107, v94, v102
	v_or_b32_e32 v102, v106, v156
	v_lshl_add_u64 v[108:109], v[102:103], 4, v[100:101]
	global_store_dword v[108:109], v107, off
.LBB0_291:
	s_or_b64 exec, exec, s[0:1]
	s_waitcnt lgkmcnt(0)
	v_mov_b32_dpp v102, v95 quad_perm:[1,0,3,2] row_mask:0xf bank_mask:0xf
	s_and_saveexec_b64 s[0:1], s[12:13]
	s_cbranch_execz .LBB0_293
	s_waitcnt lgkmcnt(0)
	v_cvt_pk_bf16_f32 v107, v95, v102
	v_or_b32_e32 v102, v106, v158
	v_lshl_add_u64 v[108:109], v[102:103], 4, v[100:101]
	global_store_dword v[108:109], v107, off
.LBB0_293:
	s_or_b64 exec, exec, s[0:1]
	s_waitcnt lgkmcnt(0)
	v_mov_b32_dpp v102, v88 quad_perm:[1,0,3,2] row_mask:0xf bank_mask:0xf
	s_and_saveexec_b64 s[0:1], s[12:13]
	s_cbranch_execz .LBB0_295
	s_waitcnt lgkmcnt(0)
	v_cvt_pk_bf16_f32 v107, v88, v102
	v_or_b32_e32 v102, v106, v160
	v_lshl_add_u64 v[108:109], v[102:103], 4, v[100:101]
	global_store_dword v[108:109], v107, off
.LBB0_295:
	s_or_b64 exec, exec, s[0:1]
	s_waitcnt lgkmcnt(0)
	v_mov_b32_dpp v102, v89 quad_perm:[1,0,3,2] row_mask:0xf bank_mask:0xf
	s_and_saveexec_b64 s[0:1], s[12:13]
	s_cbranch_execz .LBB0_297
	s_waitcnt lgkmcnt(0)
	v_cvt_pk_bf16_f32 v107, v89, v102
	v_or_b32_e32 v102, v106, v162
	v_lshl_add_u64 v[108:109], v[102:103], 4, v[100:101]
	global_store_dword v[108:109], v107, off
.LBB0_297:
	s_or_b64 exec, exec, s[0:1]
	s_waitcnt lgkmcnt(0)
	v_mov_b32_dpp v102, v90 quad_perm:[1,0,3,2] row_mask:0xf bank_mask:0xf
	s_and_saveexec_b64 s[0:1], s[12:13]
	s_cbranch_execz .LBB0_299
	s_waitcnt lgkmcnt(0)
	v_cvt_pk_bf16_f32 v107, v90, v102
	v_or_b32_e32 v102, v106, v164
	v_lshl_add_u64 v[108:109], v[102:103], 4, v[100:101]
	global_store_dword v[108:109], v107, off
; DI size_t vf_off(int h, int nblk, int krow, int d) { const int kk = krow & 31; return (((((size_t)h * nblk + (krow >> 5)) * 2 + (d >> 5)) * 2 + (kk >> 4)) * 64 + ((kk >> 2) & 1) * 32 + (d & 31)) * 8 + 4 * ((kk >> 3) & 1) + (kk & 3); }
;     DI void operator()(const AccT& acc, const Unit& u, int wr, int wc, int fr, int fq, LAS unsigned char*) const {
;     ...
;                     } else {
;                         bf16_t* vp = (bf16_t*)(ws + (isA ? WS_VTA : WS_VTB));
; #pragma unroll
;                         for (int bj = 0; bj < 2; ++bj)
; #pragma unroll
;                             for (int n = 0; n < 2; ++n)
; #pragma unroll
;                                 for (int j = 0; j < 4; ++j) {
;                                     const float mine = v[bj][n][j], oth = __shfl_xor(mine, 1);
;                                     if (!(fr & 1)) *(unsigned*)(vp + vf_off(h, krows >> 5, krow, 32 * bj + 16 * n + 4 * fq + j)) = pk2(mine, oth);
;                                 }
.LBB0_299:
	s_or_b64 exec, exec, s[0:1]
	s_waitcnt lgkmcnt(0)
	v_mov_b32_dpp v102, v91 quad_perm:[1,0,3,2] row_mask:0xf bank_mask:0xf
	s_and_saveexec_b64 s[0:1], s[12:13]
	s_cbranch_execz .LBB0_301
	s_waitcnt lgkmcnt(0)
	v_cvt_pk_bf16_f32 v108, v91, v102
	v_or_b32_e32 v102, v106, v166
	v_lshl_add_u64 v[106:107], v[102:103], 4, v[100:101]
	global_store_dword v[106:107], v108, off
.LBB0_301:
	s_or_b64 exec, exec, s[0:1]
	s_waitcnt lgkmcnt(0)
	v_mov_b32_dpp v102, v84 quad_perm:[1,0,3,2] row_mask:0xf bank_mask:0xf
	v_or_b32_e32 v105, 0xc0, v105
	s_and_saveexec_b64 s[0:1], s[12:13]
	s_cbranch_execz .LBB0_303
	s_waitcnt lgkmcnt(0)
	v_cvt_pk_bf16_f32 v108, v84, v102
	v_or_b32_e32 v102, v105, v152
	v_lshl_add_u64 v[106:107], v[102:103], 4, v[100:101]
	global_store_dword v[106:107], v108, off
.LBB0_303:
	s_or_b64 exec, exec, s[0:1]
	s_waitcnt lgkmcnt(0)
	v_mov_b32_dpp v102, v85 quad_perm:[1,0,3,2] row_mask:0xf bank_mask:0xf
	s_and_saveexec_b64 s[0:1], s[12:13]
	s_cbranch_execz .LBB0_305
	s_waitcnt lgkmcnt(0)
	v_cvt_pk_bf16_f32 v108, v85, v102
	v_or_b32_e32 v102, v105, v154
	v_lshl_add_u64 v[106:107], v[102:103], 4, v[100:101]
	global_store_dword v[106:107], v108, off
.LBB0_305:
	s_or_b64 exec, exec, s[0:1]
	s_waitcnt lgkmcnt(0)
	v_mov_b32_dpp v102, v86 quad_perm:[1,0,3,2] row_mask:0xf bank_mask:0xf
	s_and_saveexec_b64 s[0:1], s[12:13]
	s_cbranch_execz .LBB0_307
	s_waitcnt lgkmcnt(0)
	v_cvt_pk_bf16_f32 v108, v86, v102
	v_or_b32_e32 v102, v105, v156
	v_lshl_add_u64 v[106:107], v[102:103], 4, v[100:101]
	global_store_dword v[106:107], v108, off
.LBB0_307:
	s_or_b64 exec, exec, s[0:1]
	s_waitcnt lgkmcnt(0)
	v_mov_b32_dpp v102, v87 quad_perm:[1,0,3,2] row_mask:0xf bank_mask:0xf
	s_and_saveexec_b64 s[0:1], s[12:13]
	s_cbranch_execz .LBB0_309
	s_waitcnt lgkmcnt(0)
	v_cvt_pk_bf16_f32 v108, v87, v102
	v_or_b32_e32 v102, v105, v158
	v_lshl_add_u64 v[106:107], v[102:103], 4, v[100:101]
	global_store_dword v[106:107], v108, off
.LBB0_309:
	s_or_b64 exec, exec, s[0:1]
	s_waitcnt lgkmcnt(0)
	v_mov_b32_dpp v102, v80 quad_perm:[1,0,3,2] row_mask:0xf bank_mask:0xf
	s_and_saveexec_b64 s[0:1], s[12:13]
	s_cbranch_execz .LBB0_311
	s_waitcnt lgkmcnt(0)
	v_cvt_pk_bf16_f32 v108, v80, v102
	v_or_b32_e32 v102, v105, v160
	v_lshl_add_u64 v[106:107], v[102:103], 4, v[100:101]
	global_store_dword v[106:107], v108, off
.LBB0_311:
	s_or_b64 exec, exec, s[0:1]
	s_waitcnt lgkmcnt(0)
	v_mov_b32_dpp v102, v81 quad_perm:[1,0,3,2] row_mask:0xf bank_mask:0xf
	s_and_saveexec_b64 s[0:1], s[12:13]
	s_cbranch_execz .LBB0_313
	s_waitcnt lgkmcnt(0)
	v_cvt_pk_bf16_f32 v108, v81, v102
	v_or_b32_e32 v102, v105, v162
	v_lshl_add_u64 v[106:107], v[102:103], 4, v[100:101]
	global_store_dword v[106:107], v108, off
.LBB0_313:
	s_or_b64 exec, exec, s[0:1]
	s_waitcnt lgkmcnt(0)
	v_mov_b32_dpp v102, v82 quad_perm:[1,0,3,2] row_mask:0xf bank_mask:0xf
	s_and_saveexec_b64 s[0:1], s[12:13]
	s_cbranch_execz .LBB0_315
	s_waitcnt lgkmcnt(0)
	v_cvt_pk_bf16_f32 v108, v82, v102
	v_or_b32_e32 v102, v105, v164
	v_lshl_add_u64 v[106:107], v[102:103], 4, v[100:101]
	global_store_dword v[106:107], v108, off
.LBB0_315:
	s_or_b64 exec, exec, s[0:1]
	s_waitcnt lgkmcnt(0)
	v_mov_b32_dpp v102, v83 quad_perm:[1,0,3,2] row_mask:0xf bank_mask:0xf
	s_and_saveexec_b64 s[0:1], s[12:13]
	s_cbranch_execz .LBB0_317
	s_waitcnt lgkmcnt(0)
	v_cvt_pk_bf16_f32 v104, v83, v102
	v_or_b32_e32 v102, v105, v166
	v_lshl_add_u64 v[100:101], v[102:103], 4, v[100:101]
	global_store_dword v[100:101], v104, off

;     DI void operator()(const AccT& acc, const Unit& u, int wr, int wc, int fr, int fq, LAS unsigned char*) const {
;     ...
;                 if (donorm) {
;                     float ss = 0.f;
; #pragma unroll
;                     for (int bj = 0; bj < 2; ++bj)
; #pragma unroll
;                         for (int n = 0; n < 2; ++n) ss += (v[bj][n][0] * v[bj][n][0] + v[bj][n][1] * v[bj][n][1]) + (v[bj][n][2] * v[bj][n][2] + v[bj][n][3] * v[bj][n][3]);
;                     ss += __shfl_xor(ss, 16); ss += __shfl_xor(ss, 32);
;                     const float rs = rsqrtf(ss * (1.f / 64.f) + EPS);
; #pragma unroll
;                     for (int bj = 0; bj < 2; ++bj)
; #pragma unroll
;                         for (int n = 0; n < 2; ++n) v[bj][n] = v[bj][n] * rs * gv[bj][n];
;                 }
.LBB0_322:
	v_pk_mul_f32 v[80:81], v[78:79], v[78:79]
	v_pk_mul_f32 v[82:83], v[76:77], v[76:77]
	s_nop 0
	v_pk_mov_b32 v[84:85], v[82:83], v[80:81] op_sel:[1,0]
	v_mov_b32_e32 v83, v81
	v_pk_add_f32 v[80:81], v[84:85], v[82:83]
	v_pk_mul_f32 v[82:83], v[74:75], v[74:75]
	v_pk_add_f32 v[80:81], v[80:81], v[80:81] op_sel_hi:[0,1]
	v_pk_mul_f32 v[84:85], v[72:73], v[72:73]
	v_mul_f32_e32 v80, v68, v68
	v_pk_mov_b32 v[86:87], v[84:85], v[82:83] op_sel:[1,0]
	v_mov_b32_e32 v85, v83
	v_pk_add_f32 v[82:83], v[86:87], v[84:85]
	v_pk_fma_f32 v[84:85], v[68:69], v[68:69], v[80:81] op_sel_hi:[1,1,0]
	v_mul_f32_e32 v80, v70, v70
	v_pk_add_f32 v[82:83], v[82:83], v[82:83] op_sel_hi:[0,1]
	v_pk_fma_f32 v[86:87], v[70:71], v[70:71], v[80:81] op_sel_hi:[1,1,0]
	v_mul_f32_e32 v84, v64, v64
	v_mul_f32_e32 v86, v65, v65
	v_mul_f32_e32 v82, v66, v66
	v_mul_f32_e32 v80, v67, v67
	v_pk_add_f32 v[84:85], v[84:85], v[86:87]
	v_pk_add_f32 v[80:81], v[82:83], v[80:81]
	v_and_b32_e32 v82, 64, v198
	v_pk_add_f32 v[80:81], v[84:85], v[80:81]
	v_add_u32_e32 v82, 64, v82
	v_add_f32_e32 v80, v80, v81
	v_mov_b32_e32 v81, v80
	s_nop 1
	v_permlane16_swap_b32_e32 v81, v80
	v_add_f32_e32 v80, v80, v81
	v_mov_b32_e32 v81, v80
	s_nop 1
	v_permlane32_swap_b32_e32 v81, v80
	s_waitcnt lgkmcnt(0)
	v_add_f32_e32 v80, v80, v81
	v_fmamk_f32 v80, v80, 0x3c800000, v195
	v_mul_f32_e32 v81, 0x4b800000, v80
	v_cmp_gt_f32_e32 vcc, s78, v80
	s_nop 1
	v_cndmask_b32_e32 v80, v80, v81, vcc
	v_rsq_f32_e32 v80, v80
	s_nop 0
	v_mul_f32_e32 v81, 0x45800000, v80
	v_cndmask_b32_e32 v80, v80, v81, vcc
	v_pk_mul_f32 v[76:77], v[76:77], v[80:81] op_sel_hi:[1,0]
	v_pk_mul_f32 v[78:79], v[78:79], v[80:81] op_sel_hi:[1,0]
	v_pk_mul_f32 v[72:73], v[72:73], v[80:81] op_sel_hi:[1,0]
	v_pk_mul_f32 v[74:75], v[74:75], v[80:81] op_sel_hi:[1,0]
	v_pk_mul_f32 v[68:69], v[68:69], v[80:81] op_sel_hi:[1,0]
	v_pk_mul_f32 v[70:71], v[70:71], v[80:81] op_sel_hi:[1,0]
	v_pk_mul_f32 v[64:65], v[64:65], v[80:81] op_sel_hi:[1,0]
	v_pk_mul_f32 v[66:67], v[66:67], v[80:81] op_sel_hi:[1,0]
	s_waitcnt vmcnt(0)
	v_pk_mul_f32 v[78:79], v[54:55], v[78:79]
	v_pk_mul_f32 v[76:77], v[52:53], v[76:77]
	v_pk_mul_f32 v[74:75], v[50:51], v[74:75]
	v_pk_mul_f32 v[72:73], v[48:49], v[72:73]
	v_pk_mul_f32 v[70:71], v[62:63], v[70:71]
	v_pk_mul_f32 v[68:69], v[60:61], v[68:69]
	v_pk_mul_f32 v[66:67], v[58:59], v[66:67]
	v_pk_mul_f32 v[64:65], v[56:57], v[64:65]
	s_and_b64 vcc, exec, s[8:9]
	v_add_u32_e32 v80, 0x80, v182
	s_cbranch_vccz .LBB0_517

; DI u32x2 pk4(f32x4 v) { u32x2 r; r.x = pk2(v[0], v[1]); r.y = pk2(v[2], v[3]); return r; }
;     DI void operator()(const AccT& acc, const Unit& u, int wr, int wc, int fr, int fq, LAS unsigned char*) const {
;     ...
;                     const bool isA = (kind == 1 || kind == 2), isK = (kind == 1 || kind == 4);
;                     const int srow = row - SEQ;
;                     const int band = isA ? 576 : 192, past = isA ? 512 : 128, nh = isA ? 8 : 2;
;                     const int krow = row < SEQ ? row : SEQ + (srow >> 6) * band + past + (srow & 63);
;                     const int krows = isA ? KA_ROWS : KB_ROWS;
;                     float* op = nullptr;
;                     size_t ooff = 0; bool has_o = false;
;                     if (row >= SEQ) { ooff = (isA ? (isK ? OFF_AKS : OFF_AVS) : (isK ? OFF_BKS : OFF_BVS)) + ((size_t)srow * nh + h) * 64; has_o = true; }
;                     else if (row >= SEQ - past) { ooff = (isA ? (isK ? OFF_AKP : OFF_AVP) : (isK ? OFF_BKP : OFF_BVP)) + ((size_t)(row - (SEQ - past)) * nh + h) * 64; has_o = true; }
;                     op = out + ooff;
;                     if (has_o) {
; #pragma unroll
;                         for (int bj = 0; bj < 2; ++bj)
; #pragma unroll
;                             for (int n = 0; n < 2; ++n) *(f32x4*)(op + 32 * bj + 16 * n + 4 * fq) = v[bj][n];
;                     }
;                     if (isK) {
;                         bf16_t* kp = (bf16_t*)(ws + (isA ? WS_KA : WS_KB));
; #pragma unroll
;                         for (int bj = 0; bj < 2; ++bj)
; #pragma unroll
;                             for (int n = 0; n < 2; ++n) *(u32x2*)(kp + kf_off(h, krows >> 5, krow, 32 * bj + 16 * n + 4 * fq)) = pk4(v[bj][n]);
;                     } else {
;                         bf16_t* vp = (bf16_t*)(ws + (isA ? WS_VTA : WS_VTB));
; #pragma unroll
;                         for (int bj = 0; bj < 2; ++bj)
; #pragma unroll
;                             for (int n = 0; n < 2; ++n)
; #pragma unroll
;                                 for (int j = 0; j < 4; ++j) {
;                                     const float mine = v[bj][n][j], oth = __shfl_xor(mine, 1);
;                                     if (!(fr & 1)) *(unsigned*)(vp + vf_off(h, krows >> 5, krow, 32 * bj + 16 * n + 4 * fq + j)) = pk2(mine, oth);
;                                 }
.LBB0_330:
	s_or_b64 exec, exec, s[0:1]
	v_lshrrev_b32_e32 v81, 6, v81
	v_or_b32_e32 v82, s90, v167
	v_mad_u64_u32 v[82:83], s[0:1], s31, v81, v[82:83]
	v_cmp_gt_i32_e32 vcc, s68, v80
	s_mov_b64 s[0:1], -1
	s_nop 0
	v_cndmask_b32_e32 v81, v82, v80, vcc
	v_ashrrev_i32_e32 v82, 5, v81
	s_andn2_b64 vcc, exec, s[50:51]
	v_ashrrev_i32_e32 v83, 31, v82
	s_cbranch_vccnz .LBB0_364
	v_and_b32_e32 v85, 64, v198
	v_xor_b32_e32 v84, 1, v198
	v_add_u32_e32 v85, 64, v85
	v_cmp_lt_i32_e32 vcc, v84, v85
	s_add_u32 s0, s36, s91
	s_addc_u32 s1, s37, 0
	v_cndmask_b32_e32 v84, v198, v84, vcc
	v_lshlrev_b32_e32 v88, 2, v84
	v_lshlrev_b32_e32 v84, 3, v81
	v_and_b32_e32 v90, 3, v81
	v_and_b32_e32 v150, 8, v81
	v_and_b32_e32 v89, 32, v84
	v_lshl_add_u64 v[84:85], s[0:1], 0, v[150:151]
	v_lshlrev_b32_e32 v150, 1, v90
	v_mov_b32_dpp v90, v76 quad_perm:[1,0,3,2] row_mask:0xf bank_mask:0xf
	v_lshl_add_u64 v[86:87], s[46:47], 0, v[82:83]
	v_lshlrev_b32_e32 v91, 2, v81
	v_lshlrev_b64 v[86:87], 8, v[86:87]
	v_and_b32_e32 v91, 64, v91
	v_lshl_add_u64 v[84:85], v[84:85], 0, v[150:151]
	v_or3_b32 v89, v86, v91, v89
	s_and_saveexec_b64 s[0:1], s[12:13]
	s_cbranch_execz .LBB0_333
	v_or_b32_e32 v86, v89, v152
	s_waitcnt lgkmcnt(0)
	v_cvt_pk_bf16_f32 v92, v76, v90
	v_lshl_add_u64 v[90:91], v[86:87], 4, v[84:85]
	global_store_dword v[90:91], v92, off
.LBB0_333:
	s_or_b64 exec, exec, s[0:1]
	v_mov_b32_dpp v86, v77 quad_perm:[1,0,3,2] row_mask:0xf bank_mask:0xf
	s_and_saveexec_b64 s[0:1], s[12:13]
	s_cbranch_execz .LBB0_335
	s_waitcnt lgkmcnt(0)
	v_cvt_pk_bf16_f32 v92, v77, v86
	v_or_b32_e32 v86, v89, v154
	v_lshl_add_u64 v[90:91], v[86:87], 4, v[84:85]
	global_store_dword v[90:91], v92, off
.LBB0_335:
	s_or_b64 exec, exec, s[0:1]
	s_waitcnt lgkmcnt(0)
	v_mov_b32_dpp v86, v78 quad_perm:[1,0,3,2] row_mask:0xf bank_mask:0xf
	s_and_saveexec_b64 s[0:1], s[12:13]
	s_cbranch_execz .LBB0_337
	s_waitcnt lgkmcnt(0)
	v_cvt_pk_bf16_f32 v92, v78, v86
	v_or_b32_e32 v86, v89, v156
	v_lshl_add_u64 v[90:91], v[86:87], 4, v[84:85]
	global_store_dword v[90:91], v92, off
.LBB0_337:
	s_or_b64 exec, exec, s[0:1]
	s_waitcnt lgkmcnt(0)
	v_mov_b32_dpp v86, v79 quad_perm:[1,0,3,2] row_mask:0xf bank_mask:0xf
	s_and_saveexec_b64 s[0:1], s[12:13]
	s_cbranch_execz .LBB0_339
	s_waitcnt lgkmcnt(0)
	v_cvt_pk_bf16_f32 v92, v79, v86
	v_or_b32_e32 v86, v89, v158
	v_lshl_add_u64 v[90:91], v[86:87], 4, v[84:85]
	global_store_dword v[90:91], v92, off
.LBB0_339:
	s_or_b64 exec, exec, s[0:1]
	s_waitcnt lgkmcnt(0)
	v_mov_b32_dpp v86, v72 quad_perm:[1,0,3,2] row_mask:0xf bank_mask:0xf
	s_and_saveexec_b64 s[0:1], s[12:13]
	s_cbranch_execz .LBB0_341
	s_waitcnt lgkmcnt(0)
	v_cvt_pk_bf16_f32 v92, v72, v86
	v_or_b32_e32 v86, v89, v160
	v_lshl_add_u64 v[90:91], v[86:87], 4, v[84:85]
	global_store_dword v[90:91], v92, off
.LBB0_341:
	s_or_b64 exec, exec, s[0:1]
	s_waitcnt lgkmcnt(0)
	v_mov_b32_dpp v86, v73 quad_perm:[1,0,3,2] row_mask:0xf bank_mask:0xf
	s_and_saveexec_b64 s[0:1], s[12:13]
	s_cbranch_execz .LBB0_343
	s_waitcnt lgkmcnt(0)
	v_cvt_pk_bf16_f32 v92, v73, v86
	v_or_b32_e32 v86, v89, v162
	v_lshl_add_u64 v[90:91], v[86:87], 4, v[84:85]
	global_store_dword v[90:91], v92, off
.LBB0_343:
	s_or_b64 exec, exec, s[0:1]
	s_waitcnt lgkmcnt(0)
	v_mov_b32_dpp v86, v74 quad_perm:[1,0,3,2] row_mask:0xf bank_mask:0xf
	s_and_saveexec_b64 s[0:1], s[12:13]
	s_cbranch_execz .LBB0_345
	s_waitcnt lgkmcnt(0)
	v_cvt_pk_bf16_f32 v92, v74, v86
	v_or_b32_e32 v86, v89, v164
	v_lshl_add_u64 v[90:91], v[86:87], 4, v[84:85]
	global_store_dword v[90:91], v92, off
.LBB0_345:
	s_or_b64 exec, exec, s[0:1]
	s_waitcnt lgkmcnt(0)
	v_mov_b32_dpp v86, v75 quad_perm:[1,0,3,2] row_mask:0xf bank_mask:0xf
	s_and_saveexec_b64 s[0:1], s[12:13]
	s_cbranch_execz .LBB0_347
	s_waitcnt lgkmcnt(0)
	v_cvt_pk_bf16_f32 v92, v75, v86
	v_or_b32_e32 v86, v89, v166
	v_lshl_add_u64 v[90:91], v[86:87], 4, v[84:85]
	global_store_dword v[90:91], v92, off
.LBB0_347:
	s_or_b64 exec, exec, s[0:1]
	s_waitcnt lgkmcnt(0)
	v_mov_b32_dpp v86, v68 quad_perm:[1,0,3,2] row_mask:0xf bank_mask:0xf
	v_or_b32_e32 v89, 0x80, v89
	s_and_saveexec_b64 s[0:1], s[12:13]
	s_cbranch_execz .LBB0_349
	s_waitcnt lgkmcnt(0)
	v_cvt_pk_bf16_f32 v92, v68, v86
	v_or_b32_e32 v86, v89, v152
	v_lshl_add_u64 v[90:91], v[86:87], 4, v[84:85]
	global_store_dword v[90:91], v92, off
.LBB0_349:
	s_or_b64 exec, exec, s[0:1]
	s_waitcnt lgkmcnt(0)
	v_mov_b32_dpp v86, v69 quad_perm:[1,0,3,2] row_mask:0xf bank_mask:0xf
	s_and_saveexec_b64 s[0:1], s[12:13]
	s_cbranch_execz .LBB0_351
	s_waitcnt lgkmcnt(0)
	v_cvt_pk_bf16_f32 v92, v69, v86
	v_or_b32_e32 v86, v89, v154
	v_lshl_add_u64 v[90:91], v[86:87], 4, v[84:85]
	global_store_dword v[90:91], v92, off
.LBB0_351:
	s_or_b64 exec, exec, s[0:1]
	s_waitcnt lgkmcnt(0)
	v_mov_b32_dpp v86, v70 quad_perm:[1,0,3,2] row_mask:0xf bank_mask:0xf
	s_and_saveexec_b64 s[0:1], s[12:13]
	s_cbranch_execz .LBB0_353
	s_waitcnt lgkmcnt(0)
	v_cvt_pk_bf16_f32 v92, v70, v86
	v_or_b32_e32 v86, v89, v156
	v_lshl_add_u64 v[90:91], v[86:87], 4, v[84:85]
	global_store_dword v[90:91], v92, off
.LBB0_353:
	s_or_b64 exec, exec, s[0:1]
	s_waitcnt lgkmcnt(0)
	v_mov_b32_dpp v86, v71 quad_perm:[1,0,3,2] row_mask:0xf bank_mask:0xf
	s_and_saveexec_b64 s[0:1], s[12:13]
	s_cbranch_execz .LBB0_355
	s_waitcnt lgkmcnt(0)
	v_cvt_pk_bf16_f32 v92, v71, v86
	v_or_b32_e32 v86, v89, v158
	v_lshl_add_u64 v[90:91], v[86:87], 4, v[84:85]
	global_store_dword v[90:91], v92, off
.LBB0_355:
	s_or_b64 exec, exec, s[0:1]
	s_waitcnt lgkmcnt(0)
	v_mov_b32_dpp v86, v64 quad_perm:[1,0,3,2] row_mask:0xf bank_mask:0xf
	s_and_saveexec_b64 s[0:1], s[12:13]
	s_cbranch_execz .LBB0_357
	s_waitcnt lgkmcnt(0)
	v_cvt_pk_bf16_f32 v92, v64, v86
	v_or_b32_e32 v86, v89, v160
	v_lshl_add_u64 v[90:91], v[86:87], 4, v[84:85]
	global_store_dword v[90:91], v92, off
.LBB0_357:
	s_or_b64 exec, exec, s[0:1]
	s_waitcnt lgkmcnt(0)
	v_mov_b32_dpp v86, v65 quad_perm:[1,0,3,2] row_mask:0xf bank_mask:0xf
	s_and_saveexec_b64 s[0:1], s[12:13]
	s_cbranch_execz .LBB0_359
	s_waitcnt lgkmcnt(0)
	v_cvt_pk_bf16_f32 v92, v65, v86
	v_or_b32_e32 v86, v89, v162
	v_lshl_add_u64 v[90:91], v[86:87], 4, v[84:85]
	global_store_dword v[90:91], v92, off
.LBB0_359:
	s_or_b64 exec, exec, s[0:1]
	s_waitcnt lgkmcnt(0)
	v_mov_b32_dpp v86, v66 quad_perm:[1,0,3,2] row_mask:0xf bank_mask:0xf
	s_and_saveexec_b64 s[0:1], s[12:13]
	s_cbranch_execz .LBB0_361
	s_waitcnt lgkmcnt(0)
	v_cvt_pk_bf16_f32 v92, v66, v86
	v_or_b32_e32 v86, v89, v164
	v_lshl_add_u64 v[90:91], v[86:87], 4, v[84:85]
	global_store_dword v[90:91], v92, off
.LBB0_361:
	s_or_b64 exec, exec, s[0:1]
	s_waitcnt lgkmcnt(0)
	v_mov_b32_dpp v86, v67 quad_perm:[1,0,3,2] row_mask:0xf bank_mask:0xf
	s_and_saveexec_b64 s[0:1], s[12:13]
	s_cbranch_execz .LBB0_363
	s_waitcnt lgkmcnt(0)
	v_cvt_pk_bf16_f32 v88, v67, v86
	v_or_b32_e32 v86, v89, v166
	v_lshl_add_u64 v[84:85], v[86:87], 4, v[84:85]
	global_store_dword v[84:85], v88, off

;     DI void operator()(const AccT& acc, const Unit& u, int wr, int wc, int fr, int fq, LAS unsigned char*) const {
;     ...
;                 if (donorm) {
;                     float ss = 0.f;
; #pragma unroll
;                     for (int bj = 0; bj < 2; ++bj)
; #pragma unroll
;                         for (int n = 0; n < 2; ++n) ss += (v[bj][n][0] * v[bj][n][0] + v[bj][n][1] * v[bj][n][1]) + (v[bj][n][2] * v[bj][n][2] + v[bj][n][3] * v[bj][n][3]);
;                     ss += __shfl_xor(ss, 16); ss += __shfl_xor(ss, 32);
;                     const float rs = rsqrtf(ss * (1.f / 64.f) + EPS);
; #pragma unroll
;                     for (int bj = 0; bj < 2; ++bj)
; #pragma unroll
;                         for (int n = 0; n < 2; ++n) v[bj][n] = v[bj][n] * rs * gv[bj][n];
;                 }
.LBB0_368:
	v_pk_mul_f32 v[64:65], v[46:47], v[46:47]
	v_pk_mul_f32 v[66:67], v[44:45], v[44:45]
	s_nop 0
	v_pk_mov_b32 v[68:69], v[66:67], v[64:65] op_sel:[1,0]
	v_mov_b32_e32 v67, v65
	v_pk_add_f32 v[64:65], v[68:69], v[66:67]
	v_pk_mul_f32 v[66:67], v[42:43], v[42:43]
	v_pk_add_f32 v[64:65], v[64:65], v[64:65] op_sel_hi:[0,1]
	v_pk_mul_f32 v[68:69], v[40:41], v[40:41]
	v_mul_f32_e32 v64, v36, v36
	v_pk_mov_b32 v[70:71], v[68:69], v[66:67] op_sel:[1,0]
	v_mov_b32_e32 v69, v67
	v_pk_add_f32 v[66:67], v[70:71], v[68:69]
	v_pk_fma_f32 v[68:69], v[36:37], v[36:37], v[64:65] op_sel_hi:[1,1,0]
	v_mul_f32_e32 v64, v38, v38
	v_pk_add_f32 v[66:67], v[66:67], v[66:67] op_sel_hi:[0,1]
	v_pk_fma_f32 v[70:71], v[38:39], v[38:39], v[64:65] op_sel_hi:[1,1,0]
	v_mul_f32_e32 v68, v32, v32
	v_mul_f32_e32 v70, v33, v33
	v_mul_f32_e32 v66, v34, v34
	v_mul_f32_e32 v64, v35, v35
	v_pk_add_f32 v[68:69], v[68:69], v[70:71]
	v_pk_add_f32 v[64:65], v[66:67], v[64:65]
	v_and_b32_e32 v66, 64, v198
	v_pk_add_f32 v[64:65], v[68:69], v[64:65]
	v_add_u32_e32 v66, 64, v66
	v_add_f32_e32 v64, v64, v65
	v_mov_b32_e32 v65, v64
	s_nop 1
	v_permlane16_swap_b32_e32 v65, v64
	v_add_f32_e32 v64, v64, v65
	v_mov_b32_e32 v65, v64
	s_nop 1
	v_permlane32_swap_b32_e32 v65, v64
	s_waitcnt lgkmcnt(0)
	v_add_f32_e32 v64, v64, v65
	v_fmamk_f32 v64, v64, 0x3c800000, v195
	v_mul_f32_e32 v65, 0x4b800000, v64
	v_cmp_gt_f32_e32 vcc, s78, v64
	s_nop 1
	v_cndmask_b32_e32 v64, v64, v65, vcc
	v_rsq_f32_e32 v64, v64
	s_nop 0
	v_mul_f32_e32 v65, 0x45800000, v64
	v_cndmask_b32_e32 v64, v64, v65, vcc
	v_pk_mul_f32 v[44:45], v[44:45], v[64:65] op_sel_hi:[1,0]
	v_pk_mul_f32 v[46:47], v[46:47], v[64:65] op_sel_hi:[1,0]
	v_pk_mul_f32 v[40:41], v[40:41], v[64:65] op_sel_hi:[1,0]
	v_pk_mul_f32 v[42:43], v[42:43], v[64:65] op_sel_hi:[1,0]
	v_pk_mul_f32 v[36:37], v[36:37], v[64:65] op_sel_hi:[1,0]
	v_pk_mul_f32 v[38:39], v[38:39], v[64:65] op_sel_hi:[1,0]
	v_pk_mul_f32 v[32:33], v[32:33], v[64:65] op_sel_hi:[1,0]
	v_pk_mul_f32 v[34:35], v[34:35], v[64:65] op_sel_hi:[1,0]
	s_waitcnt vmcnt(0)
	v_pk_mul_f32 v[46:47], v[54:55], v[46:47]
	v_pk_mul_f32 v[44:45], v[52:53], v[44:45]
	v_pk_mul_f32 v[42:43], v[50:51], v[42:43]
	v_pk_mul_f32 v[40:41], v[48:49], v[40:41]
	v_pk_mul_f32 v[38:39], v[62:63], v[38:39]
	v_pk_mul_f32 v[36:37], v[60:61], v[36:37]
	v_pk_mul_f32 v[34:35], v[58:59], v[34:35]
	v_pk_mul_f32 v[32:33], v[56:57], v[32:33]
	s_and_b64 vcc, exec, s[8:9]
	v_add_u32_e32 v64, 0x90, v182
	s_cbranch_vccz .LBB0_521

; DI u32x2 pk4(f32x4 v) { u32x2 r; r.x = pk2(v[0], v[1]); r.y = pk2(v[2], v[3]); return r; }
;     DI void operator()(const AccT& acc, const Unit& u, int wr, int wc, int fr, int fq, LAS unsigned char*) const {
;     ...
;                     const bool isA = (kind == 1 || kind == 2), isK = (kind == 1 || kind == 4);
;                     const int srow = row - SEQ;
;                     const int band = isA ? 576 : 192, past = isA ? 512 : 128, nh = isA ? 8 : 2;
;                     const int krow = row < SEQ ? row : SEQ + (srow >> 6) * band + past + (srow & 63);
;                     const int krows = isA ? KA_ROWS : KB_ROWS;
;                     float* op = nullptr;
;                     size_t ooff = 0; bool has_o = false;
;                     if (row >= SEQ) { ooff = (isA ? (isK ? OFF_AKS : OFF_AVS) : (isK ? OFF_BKS : OFF_BVS)) + ((size_t)srow * nh + h) * 64; has_o = true; }
;                     else if (row >= SEQ - past) { ooff = (isA ? (isK ? OFF_AKP : OFF_AVP) : (isK ? OFF_BKP : OFF_BVP)) + ((size_t)(row - (SEQ - past)) * nh + h) * 64; has_o = true; }
;                     op = out + ooff;
;                     if (has_o) {
; #pragma unroll
;                         for (int bj = 0; bj < 2; ++bj)
; #pragma unroll
;                             for (int n = 0; n < 2; ++n) *(f32x4*)(op + 32 * bj + 16 * n + 4 * fq) = v[bj][n];
;                     }
;                     if (isK) {
;                         bf16_t* kp = (bf16_t*)(ws + (isA ? WS_KA : WS_KB));
; #pragma unroll
;                         for (int bj = 0; bj < 2; ++bj)
; #pragma unroll
;                             for (int n = 0; n < 2; ++n) *(u32x2*)(kp + kf_off(h, krows >> 5, krow, 32 * bj + 16 * n + 4 * fq)) = pk4(v[bj][n]);
;                     } else {
;                         bf16_t* vp = (bf16_t*)(ws + (isA ? WS_VTA : WS_VTB));
; #pragma unroll
;                         for (int bj = 0; bj < 2; ++bj)
; #pragma unroll
;                             for (int n = 0; n < 2; ++n)
; #pragma unroll
;                                 for (int j = 0; j < 4; ++j) {
;                                     const float mine = v[bj][n][j], oth = __shfl_xor(mine, 1);
;                                     if (!(fr & 1)) *(unsigned*)(vp + vf_off(h, krows >> 5, krow, 32 * bj + 16 * n + 4 * fq + j)) = pk2(mine, oth);
;                                 }
.LBB0_376:
	s_or_b64 exec, exec, s[0:1]
	v_lshrrev_b32_e32 v65, 6, v65
	v_or_b32_e32 v66, s90, v191
	v_mad_u64_u32 v[66:67], s[0:1], s31, v65, v[66:67]
	v_cmp_gt_i32_e32 vcc, s68, v64
	s_mov_b64 s[0:1], -1
	s_nop 0
	v_cndmask_b32_e32 v65, v66, v64, vcc
	v_ashrrev_i32_e32 v66, 5, v65
	s_andn2_b64 vcc, exec, s[50:51]
	v_ashrrev_i32_e32 v67, 31, v66
	s_cbranch_vccnz .LBB0_410
	v_and_b32_e32 v69, 64, v198
	v_xor_b32_e32 v68, 1, v198
	v_add_u32_e32 v69, 64, v69
	v_cmp_lt_i32_e32 vcc, v68, v69
	s_add_u32 s0, s36, s91
	s_addc_u32 s1, s37, 0
	v_cndmask_b32_e32 v68, v198, v68, vcc
	v_lshlrev_b32_e32 v72, 2, v68
	v_lshlrev_b32_e32 v68, 3, v65
	v_and_b32_e32 v74, 3, v65
	v_and_b32_e32 v150, 8, v65
	v_and_b32_e32 v73, 32, v68
	v_lshl_add_u64 v[68:69], s[0:1], 0, v[150:151]
	v_lshlrev_b32_e32 v150, 1, v74
	v_mov_b32_dpp v74, v44 quad_perm:[1,0,3,2] row_mask:0xf bank_mask:0xf
	v_lshl_add_u64 v[70:71], s[46:47], 0, v[66:67]
	v_lshlrev_b32_e32 v75, 2, v65
	v_lshlrev_b64 v[70:71], 8, v[70:71]
	v_and_b32_e32 v75, 64, v75
	v_lshl_add_u64 v[68:69], v[68:69], 0, v[150:151]
	v_or3_b32 v73, v70, v75, v73
	s_and_saveexec_b64 s[0:1], s[12:13]
	s_cbranch_execz .LBB0_379
	v_or_b32_e32 v70, v73, v152
	s_waitcnt lgkmcnt(0)
	v_cvt_pk_bf16_f32 v76, v44, v74
	v_lshl_add_u64 v[74:75], v[70:71], 4, v[68:69]
	global_store_dword v[74:75], v76, off
.LBB0_379:
	s_or_b64 exec, exec, s[0:1]
	v_mov_b32_dpp v70, v45 quad_perm:[1,0,3,2] row_mask:0xf bank_mask:0xf
	s_and_saveexec_b64 s[0:1], s[12:13]
	s_cbranch_execz .LBB0_381
	s_waitcnt lgkmcnt(0)
	v_cvt_pk_bf16_f32 v76, v45, v70
	v_or_b32_e32 v70, v73, v154
	v_lshl_add_u64 v[74:75], v[70:71], 4, v[68:69]
	global_store_dword v[74:75], v76, off
.LBB0_381:
	s_or_b64 exec, exec, s[0:1]
	s_waitcnt lgkmcnt(0)
	v_mov_b32_dpp v70, v46 quad_perm:[1,0,3,2] row_mask:0xf bank_mask:0xf
	s_and_saveexec_b64 s[0:1], s[12:13]
	s_cbranch_execz .LBB0_383
	s_waitcnt lgkmcnt(0)
	v_cvt_pk_bf16_f32 v76, v46, v70
	v_or_b32_e32 v70, v73, v156
	v_lshl_add_u64 v[74:75], v[70:71], 4, v[68:69]
	global_store_dword v[74:75], v76, off
.LBB0_383:
	s_or_b64 exec, exec, s[0:1]
	s_waitcnt lgkmcnt(0)
	v_mov_b32_dpp v70, v47 quad_perm:[1,0,3,2] row_mask:0xf bank_mask:0xf
	s_and_saveexec_b64 s[0:1], s[12:13]
	s_cbranch_execz .LBB0_385
	s_waitcnt lgkmcnt(0)
	v_cvt_pk_bf16_f32 v76, v47, v70
	v_or_b32_e32 v70, v73, v158
	v_lshl_add_u64 v[74:75], v[70:71], 4, v[68:69]
	global_store_dword v[74:75], v76, off
.LBB0_385:
	s_or_b64 exec, exec, s[0:1]
	s_waitcnt lgkmcnt(0)
	v_mov_b32_dpp v70, v40 quad_perm:[1,0,3,2] row_mask:0xf bank_mask:0xf
	s_and_saveexec_b64 s[0:1], s[12:13]
	s_cbranch_execz .LBB0_387
	s_waitcnt lgkmcnt(0)
	v_cvt_pk_bf16_f32 v76, v40, v70
	v_or_b32_e32 v70, v73, v160
	v_lshl_add_u64 v[74:75], v[70:71], 4, v[68:69]
	global_store_dword v[74:75], v76, off
.LBB0_387:
	s_or_b64 exec, exec, s[0:1]
	s_waitcnt lgkmcnt(0)
	v_mov_b32_dpp v70, v41 quad_perm:[1,0,3,2] row_mask:0xf bank_mask:0xf
	s_and_saveexec_b64 s[0:1], s[12:13]
	s_cbranch_execz .LBB0_389
	s_waitcnt lgkmcnt(0)
	v_cvt_pk_bf16_f32 v76, v41, v70
	v_or_b32_e32 v70, v73, v162
	v_lshl_add_u64 v[74:75], v[70:71], 4, v[68:69]
	global_store_dword v[74:75], v76, off
.LBB0_389:
	s_or_b64 exec, exec, s[0:1]
	s_waitcnt lgkmcnt(0)
	v_mov_b32_dpp v70, v42 quad_perm:[1,0,3,2] row_mask:0xf bank_mask:0xf
	s_and_saveexec_b64 s[0:1], s[12:13]
	s_cbranch_execz .LBB0_391
	s_waitcnt lgkmcnt(0)
	v_cvt_pk_bf16_f32 v76, v42, v70
	v_or_b32_e32 v70, v73, v164
	v_lshl_add_u64 v[74:75], v[70:71], 4, v[68:69]
	global_store_dword v[74:75], v76, off
.LBB0_391:
	s_or_b64 exec, exec, s[0:1]
	s_waitcnt lgkmcnt(0)
	v_mov_b32_dpp v70, v43 quad_perm:[1,0,3,2] row_mask:0xf bank_mask:0xf
	s_and_saveexec_b64 s[0:1], s[12:13]
	s_cbranch_execz .LBB0_393
	s_waitcnt lgkmcnt(0)
	v_cvt_pk_bf16_f32 v76, v43, v70
	v_or_b32_e32 v70, v73, v166
	v_lshl_add_u64 v[74:75], v[70:71], 4, v[68:69]
	global_store_dword v[74:75], v76, off
.LBB0_393:
	s_or_b64 exec, exec, s[0:1]
	s_waitcnt lgkmcnt(0)
	v_mov_b32_dpp v70, v36 quad_perm:[1,0,3,2] row_mask:0xf bank_mask:0xf
	v_or_b32_e32 v73, 0x80, v73
	s_and_saveexec_b64 s[0:1], s[12:13]
	s_cbranch_execz .LBB0_395
	s_waitcnt lgkmcnt(0)
	v_cvt_pk_bf16_f32 v76, v36, v70
	v_or_b32_e32 v70, v73, v152
	v_lshl_add_u64 v[74:75], v[70:71], 4, v[68:69]
	global_store_dword v[74:75], v76, off
.LBB0_395:
	s_or_b64 exec, exec, s[0:1]
	s_waitcnt lgkmcnt(0)
	v_mov_b32_dpp v70, v37 quad_perm:[1,0,3,2] row_mask:0xf bank_mask:0xf
	s_and_saveexec_b64 s[0:1], s[12:13]
	s_cbranch_execz .LBB0_397
	s_waitcnt lgkmcnt(0)
	v_cvt_pk_bf16_f32 v76, v37, v70
	v_or_b32_e32 v70, v73, v154
	v_lshl_add_u64 v[74:75], v[70:71], 4, v[68:69]
	global_store_dword v[74:75], v76, off
.LBB0_397:
	s_or_b64 exec, exec, s[0:1]
	s_waitcnt lgkmcnt(0)
	v_mov_b32_dpp v70, v38 quad_perm:[1,0,3,2] row_mask:0xf bank_mask:0xf
	s_and_saveexec_b64 s[0:1], s[12:13]
	s_cbranch_execz .LBB0_399
	s_waitcnt lgkmcnt(0)
	v_cvt_pk_bf16_f32 v76, v38, v70
	v_or_b32_e32 v70, v73, v156
	v_lshl_add_u64 v[74:75], v[70:71], 4, v[68:69]
	global_store_dword v[74:75], v76, off
.LBB0_399:
	s_or_b64 exec, exec, s[0:1]
	s_waitcnt lgkmcnt(0)
	v_mov_b32_dpp v70, v39 quad_perm:[1,0,3,2] row_mask:0xf bank_mask:0xf
	s_and_saveexec_b64 s[0:1], s[12:13]
	s_cbranch_execz .LBB0_401
	s_waitcnt lgkmcnt(0)
	v_cvt_pk_bf16_f32 v76, v39, v70
	v_or_b32_e32 v70, v73, v158
	v_lshl_add_u64 v[74:75], v[70:71], 4, v[68:69]
	global_store_dword v[74:75], v76, off
.LBB0_401:
	s_or_b64 exec, exec, s[0:1]
	s_waitcnt lgkmcnt(0)
	v_mov_b32_dpp v70, v32 quad_perm:[1,0,3,2] row_mask:0xf bank_mask:0xf
	s_and_saveexec_b64 s[0:1], s[12:13]
	s_cbranch_execz .LBB0_403
	s_waitcnt lgkmcnt(0)
	v_cvt_pk_bf16_f32 v76, v32, v70
	v_or_b32_e32 v70, v73, v160
	v_lshl_add_u64 v[74:75], v[70:71], 4, v[68:69]
	global_store_dword v[74:75], v76, off
.LBB0_403:
	s_or_b64 exec, exec, s[0:1]
	s_waitcnt lgkmcnt(0)
	v_mov_b32_dpp v70, v33 quad_perm:[1,0,3,2] row_mask:0xf bank_mask:0xf
	s_and_saveexec_b64 s[0:1], s[12:13]
	s_cbranch_execz .LBB0_405
	s_waitcnt lgkmcnt(0)
	v_cvt_pk_bf16_f32 v76, v33, v70
	v_or_b32_e32 v70, v73, v162
	v_lshl_add_u64 v[74:75], v[70:71], 4, v[68:69]
	global_store_dword v[74:75], v76, off
.LBB0_405:
	s_or_b64 exec, exec, s[0:1]
	s_waitcnt lgkmcnt(0)
	v_mov_b32_dpp v70, v34 quad_perm:[1,0,3,2] row_mask:0xf bank_mask:0xf
	s_and_saveexec_b64 s[0:1], s[12:13]
	s_cbranch_execz .LBB0_407
	s_waitcnt lgkmcnt(0)
	v_cvt_pk_bf16_f32 v76, v34, v70
	v_or_b32_e32 v70, v73, v164
	v_lshl_add_u64 v[74:75], v[70:71], 4, v[68:69]
	global_store_dword v[74:75], v76, off
.LBB0_407:
	s_or_b64 exec, exec, s[0:1]
	s_waitcnt lgkmcnt(0)
	v_mov_b32_dpp v70, v35 quad_perm:[1,0,3,2] row_mask:0xf bank_mask:0xf
	s_and_saveexec_b64 s[0:1], s[12:13]
	s_cbranch_execz .LBB0_409
	s_waitcnt lgkmcnt(0)
	v_cvt_pk_bf16_f32 v72, v35, v70
	v_or_b32_e32 v70, v73, v166
	v_lshl_add_u64 v[68:69], v[70:71], 4, v[68:69]
	global_store_dword v[68:69], v72, off

;     DI void operator()(const AccT& acc, const Unit& u, int wr, int wc, int fr, int fq, LAS unsigned char*) const {
;     ...
;                 if (donorm) {
;                     float ss = 0.f;
; #pragma unroll
;                     for (int bj = 0; bj < 2; ++bj)
; #pragma unroll
;                         for (int n = 0; n < 2; ++n) ss += (v[bj][n][0] * v[bj][n][0] + v[bj][n][1] * v[bj][n][1]) + (v[bj][n][2] * v[bj][n][2] + v[bj][n][3] * v[bj][n][3]);
;                     ss += __shfl_xor(ss, 16); ss += __shfl_xor(ss, 32);
;                     const float rs = rsqrtf(ss * (1.f / 64.f) + EPS);
; #pragma unroll
;                     for (int bj = 0; bj < 2; ++bj)
; #pragma unroll
;                         for (int n = 0; n < 2; ++n) v[bj][n] = v[bj][n] * rs * gv[bj][n];
;                 }
.LBB0_414:
	v_pk_mul_f32 v[32:33], v[30:31], v[30:31]
	v_pk_mul_f32 v[34:35], v[28:29], v[28:29]
	s_nop 0
	v_pk_mov_b32 v[36:37], v[34:35], v[32:33] op_sel:[1,0]
	v_mov_b32_e32 v35, v33
	v_pk_add_f32 v[32:33], v[36:37], v[34:35]
	v_pk_mul_f32 v[34:35], v[26:27], v[26:27]
	v_pk_add_f32 v[32:33], v[32:33], v[32:33] op_sel_hi:[0,1]
	v_pk_mul_f32 v[36:37], v[24:25], v[24:25]
	v_mul_f32_e32 v32, v20, v20
	v_pk_mov_b32 v[38:39], v[36:37], v[34:35] op_sel:[1,0]
	v_mov_b32_e32 v37, v35
	v_pk_add_f32 v[34:35], v[38:39], v[36:37]
	v_pk_fma_f32 v[36:37], v[20:21], v[20:21], v[32:33] op_sel_hi:[1,1,0]
	v_mul_f32_e32 v32, v22, v22
	v_pk_add_f32 v[34:35], v[34:35], v[34:35] op_sel_hi:[0,1]
	v_pk_fma_f32 v[38:39], v[22:23], v[22:23], v[32:33] op_sel_hi:[1,1,0]
	v_mul_f32_e32 v36, v16, v16
	v_mul_f32_e32 v38, v17, v17
	v_mul_f32_e32 v34, v18, v18
	v_mul_f32_e32 v32, v19, v19
	v_pk_add_f32 v[36:37], v[36:37], v[38:39]
	v_pk_add_f32 v[32:33], v[34:35], v[32:33]
	v_and_b32_e32 v34, 64, v198
	v_pk_add_f32 v[32:33], v[36:37], v[32:33]
	v_add_u32_e32 v34, 64, v34
	v_add_f32_e32 v32, v32, v33
	v_mov_b32_e32 v33, v32
	s_nop 1
	v_permlane16_swap_b32_e32 v33, v32
	v_add_f32_e32 v32, v32, v33
	v_mov_b32_e32 v33, v32
	s_nop 1
	v_permlane32_swap_b32_e32 v33, v32
	s_waitcnt lgkmcnt(0)
	v_add_f32_e32 v32, v32, v33
	v_fmamk_f32 v32, v32, 0x3c800000, v195
	v_mul_f32_e32 v33, 0x4b800000, v32
	v_cmp_gt_f32_e32 vcc, s78, v32
	s_nop 1
	v_cndmask_b32_e32 v32, v32, v33, vcc
	v_rsq_f32_e32 v32, v32
	s_nop 0
	v_mul_f32_e32 v33, 0x45800000, v32
	v_cndmask_b32_e32 v32, v32, v33, vcc
	v_pk_mul_f32 v[28:29], v[28:29], v[32:33] op_sel_hi:[1,0]
	v_pk_mul_f32 v[30:31], v[30:31], v[32:33] op_sel_hi:[1,0]
	v_pk_mul_f32 v[24:25], v[24:25], v[32:33] op_sel_hi:[1,0]
	v_pk_mul_f32 v[26:27], v[26:27], v[32:33] op_sel_hi:[1,0]
	v_pk_mul_f32 v[20:21], v[20:21], v[32:33] op_sel_hi:[1,0]
	v_pk_mul_f32 v[22:23], v[22:23], v[32:33] op_sel_hi:[1,0]
	v_pk_mul_f32 v[16:17], v[16:17], v[32:33] op_sel_hi:[1,0]
	v_pk_mul_f32 v[18:19], v[18:19], v[32:33] op_sel_hi:[1,0]
	s_waitcnt vmcnt(0)
	v_pk_mul_f32 v[30:31], v[54:55], v[30:31]
	v_pk_mul_f32 v[28:29], v[52:53], v[28:29]
	v_pk_mul_f32 v[26:27], v[50:51], v[26:27]
	v_pk_mul_f32 v[24:25], v[48:49], v[24:25]
	v_pk_mul_f32 v[22:23], v[62:63], v[22:23]
	v_pk_mul_f32 v[20:21], v[60:61], v[20:21]
	v_pk_mul_f32 v[18:19], v[58:59], v[18:19]
	v_pk_mul_f32 v[16:17], v[56:57], v[16:17]
	s_and_b64 vcc, exec, s[8:9]
	v_add_u32_e32 v32, 0xa0, v182
	s_cbranch_vccz .LBB0_525

; DI u32x2 pk4(f32x4 v) { u32x2 r; r.x = pk2(v[0], v[1]); r.y = pk2(v[2], v[3]); return r; }
;     DI void operator()(const AccT& acc, const Unit& u, int wr, int wc, int fr, int fq, LAS unsigned char*) const {
;     ...
;                     const bool isA = (kind == 1 || kind == 2), isK = (kind == 1 || kind == 4);
;                     const int srow = row - SEQ;
;                     const int band = isA ? 576 : 192, past = isA ? 512 : 128, nh = isA ? 8 : 2;
;                     const int krow = row < SEQ ? row : SEQ + (srow >> 6) * band + past + (srow & 63);
;                     const int krows = isA ? KA_ROWS : KB_ROWS;
;                     float* op = nullptr;
;                     size_t ooff = 0; bool has_o = false;
;                     if (row >= SEQ) { ooff = (isA ? (isK ? OFF_AKS : OFF_AVS) : (isK ? OFF_BKS : OFF_BVS)) + ((size_t)srow * nh + h) * 64; has_o = true; }
;                     else if (row >= SEQ - past) { ooff = (isA ? (isK ? OFF_AKP : OFF_AVP) : (isK ? OFF_BKP : OFF_BVP)) + ((size_t)(row - (SEQ - past)) * nh + h) * 64; has_o = true; }
;                     op = out + ooff;
;                     if (has_o) {
; #pragma unroll
;                         for (int bj = 0; bj < 2; ++bj)
; #pragma unroll
;                             for (int n = 0; n < 2; ++n) *(f32x4*)(op + 32 * bj + 16 * n + 4 * fq) = v[bj][n];
;                     }
;                     if (isK) {
;                         bf16_t* kp = (bf16_t*)(ws + (isA ? WS_KA : WS_KB));
; #pragma unroll
;                         for (int bj = 0; bj < 2; ++bj)
; #pragma unroll
;                             for (int n = 0; n < 2; ++n) *(u32x2*)(kp + kf_off(h, krows >> 5, krow, 32 * bj + 16 * n + 4 * fq)) = pk4(v[bj][n]);
;                     } else {
;                         bf16_t* vp = (bf16_t*)(ws + (isA ? WS_VTA : WS_VTB));
; #pragma unroll
;                         for (int bj = 0; bj < 2; ++bj)
; #pragma unroll
;                             for (int n = 0; n < 2; ++n)
; #pragma unroll
;                                 for (int j = 0; j < 4; ++j) {
;                                     const float mine = v[bj][n][j], oth = __shfl_xor(mine, 1);
;                                     if (!(fr & 1)) *(unsigned*)(vp + vf_off(h, krows >> 5, krow, 32 * bj + 16 * n + 4 * fq + j)) = pk2(mine, oth);
;                                 }
.LBB0_422:
	s_or_b64 exec, exec, s[0:1]
	v_lshrrev_b32_e32 v33, 6, v33
	v_or_b32_e32 v34, s90, v192
	v_mad_u64_u32 v[34:35], s[0:1], s31, v33, v[34:35]
	v_cmp_gt_i32_e32 vcc, s68, v32
	s_mov_b64 s[0:1], -1
	s_nop 0
	v_cndmask_b32_e32 v33, v34, v32, vcc
	v_ashrrev_i32_e32 v34, 5, v33
	s_andn2_b64 vcc, exec, s[50:51]
	v_ashrrev_i32_e32 v35, 31, v34
	s_cbranch_vccnz .LBB0_456
	v_and_b32_e32 v37, 64, v198
	v_xor_b32_e32 v36, 1, v198
	v_add_u32_e32 v37, 64, v37
	v_cmp_lt_i32_e32 vcc, v36, v37
	s_add_u32 s0, s36, s91
	s_addc_u32 s1, s37, 0
	v_cndmask_b32_e32 v36, v198, v36, vcc
	v_lshlrev_b32_e32 v40, 2, v36
	v_lshlrev_b32_e32 v36, 3, v33
	v_and_b32_e32 v42, 3, v33
	v_and_b32_e32 v150, 8, v33
	v_and_b32_e32 v41, 32, v36
	v_lshl_add_u64 v[36:37], s[0:1], 0, v[150:151]
	v_lshlrev_b32_e32 v150, 1, v42
	v_mov_b32_dpp v42, v28 quad_perm:[1,0,3,2] row_mask:0xf bank_mask:0xf
	v_lshl_add_u64 v[38:39], s[46:47], 0, v[34:35]
	v_lshlrev_b32_e32 v43, 2, v33
	v_lshlrev_b64 v[38:39], 8, v[38:39]
	v_and_b32_e32 v43, 64, v43
	v_lshl_add_u64 v[36:37], v[36:37], 0, v[150:151]
	v_or3_b32 v41, v38, v43, v41
	s_and_saveexec_b64 s[0:1], s[12:13]
	s_cbranch_execz .LBB0_425
	v_or_b32_e32 v38, v41, v152
	s_waitcnt lgkmcnt(0)
	v_cvt_pk_bf16_f32 v44, v28, v42
	v_lshl_add_u64 v[42:43], v[38:39], 4, v[36:37]
	global_store_dword v[42:43], v44, off
.LBB0_425:
	s_or_b64 exec, exec, s[0:1]
	v_mov_b32_dpp v38, v29 quad_perm:[1,0,3,2] row_mask:0xf bank_mask:0xf
	s_and_saveexec_b64 s[0:1], s[12:13]
	s_cbranch_execz .LBB0_427
	s_waitcnt lgkmcnt(0)
	v_cvt_pk_bf16_f32 v44, v29, v38
	v_or_b32_e32 v38, v41, v154
	v_lshl_add_u64 v[42:43], v[38:39], 4, v[36:37]
	global_store_dword v[42:43], v44, off
.LBB0_427:
	s_or_b64 exec, exec, s[0:1]
	s_waitcnt lgkmcnt(0)
	v_mov_b32_dpp v38, v30 quad_perm:[1,0,3,2] row_mask:0xf bank_mask:0xf
	s_and_saveexec_b64 s[0:1], s[12:13]
	s_cbranch_execz .LBB0_429
	s_waitcnt lgkmcnt(0)
	v_cvt_pk_bf16_f32 v44, v30, v38
	v_or_b32_e32 v38, v41, v156
	v_lshl_add_u64 v[42:43], v[38:39], 4, v[36:37]
	global_store_dword v[42:43], v44, off
.LBB0_429:
	s_or_b64 exec, exec, s[0:1]
	s_waitcnt lgkmcnt(0)
	v_mov_b32_dpp v38, v31 quad_perm:[1,0,3,2] row_mask:0xf bank_mask:0xf
	s_and_saveexec_b64 s[0:1], s[12:13]
	s_cbranch_execz .LBB0_431
	s_waitcnt lgkmcnt(0)
	v_cvt_pk_bf16_f32 v44, v31, v38
	v_or_b32_e32 v38, v41, v158
	v_lshl_add_u64 v[42:43], v[38:39], 4, v[36:37]
	global_store_dword v[42:43], v44, off
.LBB0_431:
	s_or_b64 exec, exec, s[0:1]
	s_waitcnt lgkmcnt(0)
	v_mov_b32_dpp v38, v24 quad_perm:[1,0,3,2] row_mask:0xf bank_mask:0xf
	s_and_saveexec_b64 s[0:1], s[12:13]
	s_cbranch_execz .LBB0_433
	s_waitcnt lgkmcnt(0)
	v_cvt_pk_bf16_f32 v44, v24, v38
	v_or_b32_e32 v38, v41, v160
	v_lshl_add_u64 v[42:43], v[38:39], 4, v[36:37]
	global_store_dword v[42:43], v44, off
.LBB0_433:
	s_or_b64 exec, exec, s[0:1]
	s_waitcnt lgkmcnt(0)
	v_mov_b32_dpp v38, v25 quad_perm:[1,0,3,2] row_mask:0xf bank_mask:0xf
	s_and_saveexec_b64 s[0:1], s[12:13]
	s_cbranch_execz .LBB0_435
	s_waitcnt lgkmcnt(0)
	v_cvt_pk_bf16_f32 v44, v25, v38
	v_or_b32_e32 v38, v41, v162
	v_lshl_add_u64 v[42:43], v[38:39], 4, v[36:37]
	global_store_dword v[42:43], v44, off
.LBB0_435:
	s_or_b64 exec, exec, s[0:1]
	s_waitcnt lgkmcnt(0)
	v_mov_b32_dpp v38, v26 quad_perm:[1,0,3,2] row_mask:0xf bank_mask:0xf
	s_and_saveexec_b64 s[0:1], s[12:13]
	s_cbranch_execz .LBB0_437
	s_waitcnt lgkmcnt(0)
	v_cvt_pk_bf16_f32 v44, v26, v38
	v_or_b32_e32 v38, v41, v164
	v_lshl_add_u64 v[42:43], v[38:39], 4, v[36:37]
	global_store_dword v[42:43], v44, off
.LBB0_437:
	s_or_b64 exec, exec, s[0:1]
	s_waitcnt lgkmcnt(0)
	v_mov_b32_dpp v38, v27 quad_perm:[1,0,3,2] row_mask:0xf bank_mask:0xf
	s_and_saveexec_b64 s[0:1], s[12:13]
	s_cbranch_execz .LBB0_439
	s_waitcnt lgkmcnt(0)
	v_cvt_pk_bf16_f32 v44, v27, v38
	v_or_b32_e32 v38, v41, v166
	v_lshl_add_u64 v[42:43], v[38:39], 4, v[36:37]
	global_store_dword v[42:43], v44, off
.LBB0_439:
	s_or_b64 exec, exec, s[0:1]
	s_waitcnt lgkmcnt(0)
	v_mov_b32_dpp v38, v20 quad_perm:[1,0,3,2] row_mask:0xf bank_mask:0xf
	v_or_b32_e32 v41, 0x80, v41
	s_and_saveexec_b64 s[0:1], s[12:13]
	s_cbranch_execz .LBB0_441
	s_waitcnt lgkmcnt(0)
	v_cvt_pk_bf16_f32 v44, v20, v38
	v_or_b32_e32 v38, v41, v152
	v_lshl_add_u64 v[42:43], v[38:39], 4, v[36:37]
	global_store_dword v[42:43], v44, off
.LBB0_441:
	s_or_b64 exec, exec, s[0:1]
	s_waitcnt lgkmcnt(0)
	v_mov_b32_dpp v38, v21 quad_perm:[1,0,3,2] row_mask:0xf bank_mask:0xf
	s_and_saveexec_b64 s[0:1], s[12:13]
	s_cbranch_execz .LBB0_443
	s_waitcnt lgkmcnt(0)
	v_cvt_pk_bf16_f32 v44, v21, v38
	v_or_b32_e32 v38, v41, v154
	v_lshl_add_u64 v[42:43], v[38:39], 4, v[36:37]
	global_store_dword v[42:43], v44, off
.LBB0_443:
	s_or_b64 exec, exec, s[0:1]
	s_waitcnt lgkmcnt(0)
	v_mov_b32_dpp v38, v22 quad_perm:[1,0,3,2] row_mask:0xf bank_mask:0xf
	s_and_saveexec_b64 s[0:1], s[12:13]
	s_cbranch_execz .LBB0_445
	s_waitcnt lgkmcnt(0)
	v_cvt_pk_bf16_f32 v44, v22, v38
	v_or_b32_e32 v38, v41, v156
	v_lshl_add_u64 v[42:43], v[38:39], 4, v[36:37]
	global_store_dword v[42:43], v44, off
.LBB0_445:
	s_or_b64 exec, exec, s[0:1]
	s_waitcnt lgkmcnt(0)
	v_mov_b32_dpp v38, v23 quad_perm:[1,0,3,2] row_mask:0xf bank_mask:0xf
	s_and_saveexec_b64 s[0:1], s[12:13]
	s_cbranch_execz .LBB0_447
	s_waitcnt lgkmcnt(0)
	v_cvt_pk_bf16_f32 v44, v23, v38
	v_or_b32_e32 v38, v41, v158
	v_lshl_add_u64 v[42:43], v[38:39], 4, v[36:37]
	global_store_dword v[42:43], v44, off
.LBB0_447:
	s_or_b64 exec, exec, s[0:1]
	s_waitcnt lgkmcnt(0)
	v_mov_b32_dpp v38, v16 quad_perm:[1,0,3,2] row_mask:0xf bank_mask:0xf
	s_and_saveexec_b64 s[0:1], s[12:13]
	s_cbranch_execz .LBB0_449
	s_waitcnt lgkmcnt(0)
	v_cvt_pk_bf16_f32 v44, v16, v38
	v_or_b32_e32 v38, v41, v160
	v_lshl_add_u64 v[42:43], v[38:39], 4, v[36:37]
	global_store_dword v[42:43], v44, off
.LBB0_449:
	s_or_b64 exec, exec, s[0:1]
	s_waitcnt lgkmcnt(0)
	v_mov_b32_dpp v38, v17 quad_perm:[1,0,3,2] row_mask:0xf bank_mask:0xf
	s_and_saveexec_b64 s[0:1], s[12:13]
	s_cbranch_execz .LBB0_451
	s_waitcnt lgkmcnt(0)
	v_cvt_pk_bf16_f32 v44, v17, v38
	v_or_b32_e32 v38, v41, v162
	v_lshl_add_u64 v[42:43], v[38:39], 4, v[36:37]
	global_store_dword v[42:43], v44, off
.LBB0_451:
	s_or_b64 exec, exec, s[0:1]
	s_waitcnt lgkmcnt(0)
	v_mov_b32_dpp v38, v18 quad_perm:[1,0,3,2] row_mask:0xf bank_mask:0xf
	s_and_saveexec_b64 s[0:1], s[12:13]
	s_cbranch_execz .LBB0_453
	s_waitcnt lgkmcnt(0)
	v_cvt_pk_bf16_f32 v44, v18, v38
	v_or_b32_e32 v38, v41, v164
	v_lshl_add_u64 v[42:43], v[38:39], 4, v[36:37]
	global_store_dword v[42:43], v44, off
.LBB0_453:
	s_or_b64 exec, exec, s[0:1]
	s_waitcnt lgkmcnt(0)
	v_mov_b32_dpp v38, v19 quad_perm:[1,0,3,2] row_mask:0xf bank_mask:0xf
	s_and_saveexec_b64 s[0:1], s[12:13]
	s_cbranch_execz .LBB0_455
	s_waitcnt lgkmcnt(0)
	v_cvt_pk_bf16_f32 v40, v19, v38
	v_or_b32_e32 v38, v41, v166
	v_lshl_add_u64 v[36:37], v[38:39], 4, v[36:37]
	global_store_dword v[36:37], v40, off

;     DI void operator()(const AccT& acc, const Unit& u, int wr, int wc, int fr, int fq, LAS unsigned char*) const {
;     ...
;                 if (donorm) {
;                     float ss = 0.f;
; #pragma unroll
;                     for (int bj = 0; bj < 2; ++bj)
; #pragma unroll
;                         for (int n = 0; n < 2; ++n) ss += (v[bj][n][0] * v[bj][n][0] + v[bj][n][1] * v[bj][n][1]) + (v[bj][n][2] * v[bj][n][2] + v[bj][n][3] * v[bj][n][3]);
;                     ss += __shfl_xor(ss, 16); ss += __shfl_xor(ss, 32);
;                     const float rs = rsqrtf(ss * (1.f / 64.f) + EPS);
; #pragma unroll
;                     for (int bj = 0; bj < 2; ++bj)
; #pragma unroll
;                         for (int n = 0; n < 2; ++n) v[bj][n] = v[bj][n] * rs * gv[bj][n];
;                 }
.LBB0_460:
	v_pk_mul_f32 v[16:17], v[14:15], v[14:15]
	v_pk_mul_f32 v[18:19], v[12:13], v[12:13]
	s_nop 0
	v_pk_mov_b32 v[20:21], v[18:19], v[16:17] op_sel:[1,0]
	v_mov_b32_e32 v19, v17
	v_pk_add_f32 v[16:17], v[20:21], v[18:19]
	v_pk_mul_f32 v[18:19], v[10:11], v[10:11]
	v_pk_add_f32 v[16:17], v[16:17], v[16:17] op_sel_hi:[0,1]
	v_pk_mul_f32 v[20:21], v[8:9], v[8:9]
	v_mul_f32_e32 v16, v4, v4
	v_pk_mov_b32 v[22:23], v[20:21], v[18:19] op_sel:[1,0]
	v_mov_b32_e32 v21, v19
	v_pk_add_f32 v[18:19], v[22:23], v[20:21]
	v_pk_fma_f32 v[20:21], v[4:5], v[4:5], v[16:17] op_sel_hi:[1,1,0]
	v_mul_f32_e32 v16, v6, v6
	v_pk_add_f32 v[18:19], v[18:19], v[18:19] op_sel_hi:[0,1]
	v_pk_fma_f32 v[22:23], v[6:7], v[6:7], v[16:17] op_sel_hi:[1,1,0]
	v_mul_f32_e32 v20, v0, v0
	v_mul_f32_e32 v22, v1, v1
	v_mul_f32_e32 v18, v2, v2
	v_mul_f32_e32 v16, v3, v3
	v_pk_add_f32 v[20:21], v[20:21], v[22:23]
	v_pk_add_f32 v[16:17], v[18:19], v[16:17]
	v_and_b32_e32 v18, 64, v198
	v_pk_add_f32 v[16:17], v[20:21], v[16:17]
	v_add_u32_e32 v18, 64, v18
	v_add_f32_e32 v16, v16, v17
	v_mov_b32_e32 v17, v16
	s_nop 1
	v_permlane16_swap_b32_e32 v17, v16
	v_add_f32_e32 v16, v16, v17
	v_mov_b32_e32 v17, v16
	s_nop 1
	v_permlane32_swap_b32_e32 v17, v16
	s_waitcnt lgkmcnt(0)
	v_add_f32_e32 v16, v16, v17
	v_fmamk_f32 v16, v16, 0x3c800000, v195
	v_mul_f32_e32 v17, 0x4b800000, v16
	v_cmp_gt_f32_e32 vcc, s78, v16
	s_nop 1
	v_cndmask_b32_e32 v16, v16, v17, vcc
	v_rsq_f32_e32 v16, v16
	s_nop 0
	v_mul_f32_e32 v17, 0x45800000, v16
	v_cndmask_b32_e32 v16, v16, v17, vcc
	v_pk_mul_f32 v[12:13], v[12:13], v[16:17] op_sel_hi:[1,0]
	v_pk_mul_f32 v[14:15], v[14:15], v[16:17] op_sel_hi:[1,0]
	v_pk_mul_f32 v[8:9], v[8:9], v[16:17] op_sel_hi:[1,0]
	v_pk_mul_f32 v[10:11], v[10:11], v[16:17] op_sel_hi:[1,0]
	v_pk_mul_f32 v[4:5], v[4:5], v[16:17] op_sel_hi:[1,0]
	v_pk_mul_f32 v[6:7], v[6:7], v[16:17] op_sel_hi:[1,0]
	v_pk_mul_f32 v[0:1], v[0:1], v[16:17] op_sel_hi:[1,0]
	v_pk_mul_f32 v[2:3], v[2:3], v[16:17] op_sel_hi:[1,0]
	s_waitcnt vmcnt(0)
	v_pk_mul_f32 v[14:15], v[54:55], v[14:15]
	v_pk_mul_f32 v[12:13], v[52:53], v[12:13]
	v_pk_mul_f32 v[10:11], v[50:51], v[10:11]
	v_pk_mul_f32 v[8:9], v[48:49], v[8:9]
	v_pk_mul_f32 v[6:7], v[62:63], v[6:7]
	v_pk_mul_f32 v[4:5], v[60:61], v[4:5]
	v_pk_mul_f32 v[2:3], v[58:59], v[2:3]
	v_pk_mul_f32 v[0:1], v[56:57], v[0:1]
	s_and_b64 vcc, exec, s[8:9]
	v_add_u32_e32 v16, 0xb0, v182
	s_cbranch_vccz .LBB0_529

; DI u32x2 pk4(f32x4 v) { u32x2 r; r.x = pk2(v[0], v[1]); r.y = pk2(v[2], v[3]); return r; }
;     DI void operator()(const AccT& acc, const Unit& u, int wr, int wc, int fr, int fq, LAS unsigned char*) const {
;     ...
;                     const bool isA = (kind == 1 || kind == 2), isK = (kind == 1 || kind == 4);
;                     const int srow = row - SEQ;
;                     const int band = isA ? 576 : 192, past = isA ? 512 : 128, nh = isA ? 8 : 2;
;                     const int krow = row < SEQ ? row : SEQ + (srow >> 6) * band + past + (srow & 63);
;                     const int krows = isA ? KA_ROWS : KB_ROWS;
;                     float* op = nullptr;
;                     size_t ooff = 0; bool has_o = false;
;                     if (row >= SEQ) { ooff = (isA ? (isK ? OFF_AKS : OFF_AVS) : (isK ? OFF_BKS : OFF_BVS)) + ((size_t)srow * nh + h) * 64; has_o = true; }
;                     else if (row >= SEQ - past) { ooff = (isA ? (isK ? OFF_AKP : OFF_AVP) : (isK ? OFF_BKP : OFF_BVP)) + ((size_t)(row - (SEQ - past)) * nh + h) * 64; has_o = true; }
;                     op = out + ooff;
;                     if (has_o) {
; #pragma unroll
;                         for (int bj = 0; bj < 2; ++bj)
; #pragma unroll
;                             for (int n = 0; n < 2; ++n) *(f32x4*)(op + 32 * bj + 16 * n + 4 * fq) = v[bj][n];
;                     }
;                     if (isK) {
;                         bf16_t* kp = (bf16_t*)(ws + (isA ? WS_KA : WS_KB));
; #pragma unroll
;                         for (int bj = 0; bj < 2; ++bj)
; #pragma unroll
;                             for (int n = 0; n < 2; ++n) *(u32x2*)(kp + kf_off(h, krows >> 5, krow, 32 * bj + 16 * n + 4 * fq)) = pk4(v[bj][n]);
;                     } else {
;                         bf16_t* vp = (bf16_t*)(ws + (isA ? WS_VTA : WS_VTB));
; #pragma unroll
;                         for (int bj = 0; bj < 2; ++bj)
; #pragma unroll
;                             for (int n = 0; n < 2; ++n)
; #pragma unroll
;                                 for (int j = 0; j < 4; ++j) {
;                                     const float mine = v[bj][n][j], oth = __shfl_xor(mine, 1);
;                                     if (!(fr & 1)) *(unsigned*)(vp + vf_off(h, krows >> 5, krow, 32 * bj + 16 * n + 4 * fq + j)) = pk2(mine, oth);
;                                 }
.LBB0_468:
	s_or_b64 exec, exec, s[0:1]
	v_lshrrev_b32_e32 v17, 6, v17
	v_or_b32_e32 v18, s90, v193
	v_mad_u64_u32 v[18:19], s[0:1], s31, v17, v[18:19]
	v_cmp_gt_i32_e32 vcc, s68, v16
	s_mov_b64 s[0:1], -1
	s_nop 0
	v_cndmask_b32_e32 v17, v18, v16, vcc
	v_ashrrev_i32_e32 v18, 5, v17
	s_andn2_b64 vcc, exec, s[50:51]
	v_ashrrev_i32_e32 v19, 31, v18
	s_cbranch_vccnz .LBB0_502
	v_and_b32_e32 v21, 64, v198
	v_xor_b32_e32 v20, 1, v198
	v_add_u32_e32 v21, 64, v21
	v_cmp_lt_i32_e32 vcc, v20, v21
	s_add_u32 s0, s36, s91
	s_addc_u32 s1, s37, 0
	v_cndmask_b32_e32 v20, v198, v20, vcc
	v_lshlrev_b32_e32 v24, 2, v20
	v_lshlrev_b32_e32 v20, 3, v17
	v_and_b32_e32 v26, 3, v17
	v_and_b32_e32 v150, 8, v17
	v_and_b32_e32 v25, 32, v20
	v_lshl_add_u64 v[20:21], s[0:1], 0, v[150:151]
	v_lshlrev_b32_e32 v150, 1, v26
	v_mov_b32_dpp v26, v12 quad_perm:[1,0,3,2] row_mask:0xf bank_mask:0xf
	v_lshl_add_u64 v[22:23], s[46:47], 0, v[18:19]
	v_lshlrev_b32_e32 v27, 2, v17
	v_lshlrev_b64 v[22:23], 8, v[22:23]
	v_and_b32_e32 v27, 64, v27
	v_lshl_add_u64 v[20:21], v[20:21], 0, v[150:151]
	v_or3_b32 v25, v22, v27, v25
	s_and_saveexec_b64 s[0:1], s[12:13]
	s_cbranch_execz .LBB0_471
	v_or_b32_e32 v22, v25, v152
	s_waitcnt lgkmcnt(0)
	v_cvt_pk_bf16_f32 v28, v12, v26
	v_lshl_add_u64 v[26:27], v[22:23], 4, v[20:21]
	global_store_dword v[26:27], v28, off
.LBB0_471:
	s_or_b64 exec, exec, s[0:1]
	v_mov_b32_dpp v22, v13 quad_perm:[1,0,3,2] row_mask:0xf bank_mask:0xf
	s_and_saveexec_b64 s[0:1], s[12:13]
	s_cbranch_execz .LBB0_473
	s_waitcnt lgkmcnt(0)
	v_cvt_pk_bf16_f32 v28, v13, v22
	v_or_b32_e32 v22, v25, v154
	v_lshl_add_u64 v[26:27], v[22:23], 4, v[20:21]
	global_store_dword v[26:27], v28, off
.LBB0_473:
	s_or_b64 exec, exec, s[0:1]
	s_waitcnt lgkmcnt(0)
	v_mov_b32_dpp v22, v14 quad_perm:[1,0,3,2] row_mask:0xf bank_mask:0xf
	s_and_saveexec_b64 s[0:1], s[12:13]
	s_cbranch_execz .LBB0_475
	s_waitcnt lgkmcnt(0)
	v_cvt_pk_bf16_f32 v28, v14, v22
	v_or_b32_e32 v22, v25, v156
	v_lshl_add_u64 v[26:27], v[22:23], 4, v[20:21]
	global_store_dword v[26:27], v28, off
.LBB0_475:
	s_or_b64 exec, exec, s[0:1]
	s_waitcnt lgkmcnt(0)
	v_mov_b32_dpp v22, v15 quad_perm:[1,0,3,2] row_mask:0xf bank_mask:0xf
	s_and_saveexec_b64 s[0:1], s[12:13]
	s_cbranch_execz .LBB0_477
	s_waitcnt lgkmcnt(0)
	v_cvt_pk_bf16_f32 v28, v15, v22
	v_or_b32_e32 v22, v25, v158
	v_lshl_add_u64 v[26:27], v[22:23], 4, v[20:21]
	global_store_dword v[26:27], v28, off
.LBB0_477:
	s_or_b64 exec, exec, s[0:1]
	s_waitcnt lgkmcnt(0)
	v_mov_b32_dpp v22, v8 quad_perm:[1,0,3,2] row_mask:0xf bank_mask:0xf
	s_and_saveexec_b64 s[0:1], s[12:13]
	s_cbranch_execz .LBB0_479
	s_waitcnt lgkmcnt(0)
	v_cvt_pk_bf16_f32 v28, v8, v22
	v_or_b32_e32 v22, v25, v160
	v_lshl_add_u64 v[26:27], v[22:23], 4, v[20:21]
	global_store_dword v[26:27], v28, off
.LBB0_479:
	s_or_b64 exec, exec, s[0:1]
	s_waitcnt lgkmcnt(0)
	v_mov_b32_dpp v22, v9 quad_perm:[1,0,3,2] row_mask:0xf bank_mask:0xf
	s_and_saveexec_b64 s[0:1], s[12:13]
	s_cbranch_execz .LBB0_481
	s_waitcnt lgkmcnt(0)
	v_cvt_pk_bf16_f32 v28, v9, v22
	v_or_b32_e32 v22, v25, v162
	v_lshl_add_u64 v[26:27], v[22:23], 4, v[20:21]
	global_store_dword v[26:27], v28, off
.LBB0_481:
	s_or_b64 exec, exec, s[0:1]
	s_waitcnt lgkmcnt(0)
	v_mov_b32_dpp v22, v10 quad_perm:[1,0,3,2] row_mask:0xf bank_mask:0xf
	s_and_saveexec_b64 s[0:1], s[12:13]
	s_cbranch_execz .LBB0_483
	s_waitcnt lgkmcnt(0)
	v_cvt_pk_bf16_f32 v28, v10, v22
	v_or_b32_e32 v22, v25, v164
	v_lshl_add_u64 v[26:27], v[22:23], 4, v[20:21]
	global_store_dword v[26:27], v28, off
.LBB0_483:
	s_or_b64 exec, exec, s[0:1]
	s_waitcnt lgkmcnt(0)
	v_mov_b32_dpp v22, v11 quad_perm:[1,0,3,2] row_mask:0xf bank_mask:0xf
	s_and_saveexec_b64 s[0:1], s[12:13]
	s_cbranch_execz .LBB0_485
	s_waitcnt lgkmcnt(0)
	v_cvt_pk_bf16_f32 v28, v11, v22
	v_or_b32_e32 v22, v25, v166
	v_lshl_add_u64 v[26:27], v[22:23], 4, v[20:21]
	global_store_dword v[26:27], v28, off
.LBB0_485:
	s_or_b64 exec, exec, s[0:1]
	s_waitcnt lgkmcnt(0)
	v_mov_b32_dpp v22, v4 quad_perm:[1,0,3,2] row_mask:0xf bank_mask:0xf
	v_or_b32_e32 v25, 0x80, v25
	s_and_saveexec_b64 s[0:1], s[12:13]
	s_cbranch_execz .LBB0_487
	s_waitcnt lgkmcnt(0)
	v_cvt_pk_bf16_f32 v28, v4, v22
	v_or_b32_e32 v22, v25, v152
	v_lshl_add_u64 v[26:27], v[22:23], 4, v[20:21]
	global_store_dword v[26:27], v28, off
.LBB0_487:
	s_or_b64 exec, exec, s[0:1]
	s_waitcnt lgkmcnt(0)
	v_mov_b32_dpp v22, v5 quad_perm:[1,0,3,2] row_mask:0xf bank_mask:0xf
	s_and_saveexec_b64 s[0:1], s[12:13]
	s_cbranch_execz .LBB0_489
	s_waitcnt lgkmcnt(0)
	v_cvt_pk_bf16_f32 v28, v5, v22
	v_or_b32_e32 v22, v25, v154
	v_lshl_add_u64 v[26:27], v[22:23], 4, v[20:21]
	global_store_dword v[26:27], v28, off
.LBB0_489:
	s_or_b64 exec, exec, s[0:1]
	s_waitcnt lgkmcnt(0)
	v_mov_b32_dpp v22, v6 quad_perm:[1,0,3,2] row_mask:0xf bank_mask:0xf
	s_and_saveexec_b64 s[0:1], s[12:13]
	s_cbranch_execz .LBB0_491
	s_waitcnt lgkmcnt(0)
	v_cvt_pk_bf16_f32 v28, v6, v22
	v_or_b32_e32 v22, v25, v156
	v_lshl_add_u64 v[26:27], v[22:23], 4, v[20:21]
	global_store_dword v[26:27], v28, off
.LBB0_491:
	s_or_b64 exec, exec, s[0:1]
	s_waitcnt lgkmcnt(0)
	v_mov_b32_dpp v22, v7 quad_perm:[1,0,3,2] row_mask:0xf bank_mask:0xf
	s_and_saveexec_b64 s[0:1], s[12:13]
	s_cbranch_execz .LBB0_493
	s_waitcnt lgkmcnt(0)
	v_cvt_pk_bf16_f32 v28, v7, v22
	v_or_b32_e32 v22, v25, v158
	v_lshl_add_u64 v[26:27], v[22:23], 4, v[20:21]
	global_store_dword v[26:27], v28, off
.LBB0_493:
	s_or_b64 exec, exec, s[0:1]
	s_waitcnt lgkmcnt(0)
	v_mov_b32_dpp v22, v0 quad_perm:[1,0,3,2] row_mask:0xf bank_mask:0xf
	s_and_saveexec_b64 s[0:1], s[12:13]
	s_cbranch_execz .LBB0_495
	s_waitcnt lgkmcnt(0)
	v_cvt_pk_bf16_f32 v28, v0, v22
	v_or_b32_e32 v22, v25, v160
	v_lshl_add_u64 v[26:27], v[22:23], 4, v[20:21]
	global_store_dword v[26:27], v28, off
.LBB0_495:
	s_or_b64 exec, exec, s[0:1]
	s_waitcnt lgkmcnt(0)
	v_mov_b32_dpp v22, v1 quad_perm:[1,0,3,2] row_mask:0xf bank_mask:0xf
	s_and_saveexec_b64 s[0:1], s[12:13]
	s_cbranch_execz .LBB0_497
	s_waitcnt lgkmcnt(0)
	v_cvt_pk_bf16_f32 v28, v1, v22
	v_or_b32_e32 v22, v25, v162
	v_lshl_add_u64 v[26:27], v[22:23], 4, v[20:21]
	global_store_dword v[26:27], v28, off
.LBB0_497:
	s_or_b64 exec, exec, s[0:1]
	s_waitcnt lgkmcnt(0)
	v_mov_b32_dpp v22, v2 quad_perm:[1,0,3,2] row_mask:0xf bank_mask:0xf
	s_and_saveexec_b64 s[0:1], s[12:13]
	s_cbranch_execz .LBB0_499
	s_waitcnt lgkmcnt(0)
	v_cvt_pk_bf16_f32 v28, v2, v22
	v_or_b32_e32 v22, v25, v164
	v_lshl_add_u64 v[26:27], v[22:23], 4, v[20:21]
	global_store_dword v[26:27], v28, off
.LBB0_499:
	s_or_b64 exec, exec, s[0:1]
	s_waitcnt lgkmcnt(0)
	v_mov_b32_dpp v22, v3 quad_perm:[1,0,3,2] row_mask:0xf bank_mask:0xf
	s_and_saveexec_b64 s[0:1], s[12:13]
	s_cbranch_execz .LBB0_501
	s_waitcnt lgkmcnt(0)
	v_cvt_pk_bf16_f32 v24, v3, v22
	v_or_b32_e32 v22, v25, v166
	v_lshl_add_u64 v[20:21], v[22:23], 4, v[20:21]
	global_store_dword v[20:21], v24, off
